# version 97 plus nt (non-temporal) hint on the read-once streaming loads of the weight / input conversion code (prologue phase and side conversions)
# speedup vs baseline: 1.0116x; 1.0104x over previous
; __device__ __forceinline__ CvtItem cvt_decode(const Args& A, const int it) {
;     ...
;     const int kb = r / nblk, nb = r % nblk; c.k0 = 64 * kb; c.n0 = 32 * nb; c.spec = (kind == 2) && (c.n0 >= 3072);
;     c.W = W0; c.col0 = c.n0;
;     if (kind == 0) { const int pn = c.n0 >> 8, bj = (c.n0 >> 7) & 1, jj = c.n0 & 127; c.W = bj ? W1 : W0; c.col0 = pn * 128 + jj; }
;     if (kind == 2) c.col0 = (c.n0 < 1024) ? c.n0 : c.n0 + 16;
;     return c;
; }
; __device__ __forceinline__ void cvt_load(const CvtItem& c, const int lane, f32x4 (&vv)[8], float (&gv)[8]) {
;     const int kr = lane >> 3, nq = lane & 7;
;     if (!c.spec) {
; #pragma unroll
;         for (int i = 0; i < 8; ++i) vv[i] = *(const f32x4*)(c.W + (size_t)(c.k0 + 8 * i + kr) * c.Nsrc + c.col0 + 4 * nq);
; #pragma unroll
;         for (int i = 0; i < 8; ++i) gv[i] = c.gain ? c.gain[c.k0 + 8 * i + kr] : 1.0f;
.LBB0_657:
	s_sext_i32_i16 s0, s18
	s_waitcnt vmcnt(6)
	v_cvt_f32_i32_e32 v5, s0
	s_sext_i32_i16 s1, s17
	s_waitcnt vmcnt(0)
	v_cvt_f32_i32_e32 v8, s1
	s_xor_b32 s0, s1, s0
	s_waitcnt lgkmcnt(0)
	v_rcp_iflag_f32_e32 v9, v5
	s_ashr_i32 s0, s0, 30
	s_or_b32 s8, s0, 1
	v_and_b32_e32 v20, 63, v244
	v_mul_f32_e32 v9, v8, v9
	v_trunc_f32_e32 v9, v9
	v_fma_f32 v8, -v9, v5, v8
	v_cvt_i32_f32_e32 v9, v9
	v_cmp_ge_f32_e64 s[0:1], |v8|, |v5|
	s_and_b64 s[0:1], s[0:1], exec
	s_cselect_b32 s0, s8, 0
	v_readfirstlane_b32 s1, v9
	s_add_i32 s0, s1, s0
	s_sext_i32_i16 s15, s0
	s_mul_i32 s0, s0, s18
	s_sub_i32 s8, s17, s0
	s_sext_i32_i16 s14, s8
	s_lshl_b32 s45, s14, 5
	s_cmpk_gt_i32 s14, 0x5f
	s_cselect_b64 s[0:1], -1, 0
	s_bitcmp0_b32 s8, 2
	s_cselect_b64 vcc, -1, 0
	v_cndmask_b32_e32 v5, v6, v2, vcc
	v_cndmask_b32_e32 v6, v7, v3, vcc
	v_cndmask_b32_e64 v86, v2, v5, s[10:11]
	s_and_b64 s[8:9], s[12:13], s[0:1]
	v_lshlrev_b32_e32 v2, 2, v20
	v_cndmask_b32_e64 v87, v3, v6, s[10:11]
	s_lshl_b32 s20, s15, 6
	s_mov_b64 s[0:1], -1
	s_andn2_b64 vcc, exec, s[8:9]
	v_lshrrev_b32_e32 v21, 3, v20
	v_and_b32_e32 v14, 28, v2
	s_cbranch_vccz .LBB0_669
	s_or_b32 s0, s45, 16
	s_cmp_lt_i32 s14, 32
	s_cselect_b32 s15, s45, s0
	s_lshl_b32 s0, s14, 4
	s_and_b32 s0, s0, 0xffffff80
	s_and_b32 s1, s45, 0x60
	s_or_b32 s14, s0, s1
	s_and_b64 s[0:1], s[10:11], exec
	s_cselect_b32 s10, s14, s45
	s_and_b64 s[0:1], s[12:13], exec
	v_lshrrev_b32_e32 v96, 3, v20
	s_cselect_b32 s0, s15, s10
	v_and_b32_e32 v16, 28, v2
	v_or_b32_e32 v2, s20, v96
	v_mul_hi_i32_i24_e32 v7, s43, v2
	v_mul_i32_i24_e32 v6, s43, v2
	s_ashr_i32 s1, s0, 31
	v_or_b32_e32 v3, 8, v2
	v_lshl_add_u64 v[6:7], v[6:7], 2, v[86:87]
	s_lshl_b64 s[0:1], s[0:1], 2
	v_mul_hi_i32_i24_e32 v11, s43, v3
	v_mul_i32_i24_e32 v10, s43, v3
	v_lshl_add_u64 v[6:7], v[6:7], 0, s[0:1]
	v_lshlrev_b32_e32 v8, 2, v16
	v_mov_b32_e32 v9, v4
	v_lshl_add_u64 v[10:11], v[10:11], 2, v[86:87]
	v_lshl_add_u64 v[6:7], v[6:7], 0, v[8:9]
	v_lshl_add_u64 v[10:11], v[10:11], 0, s[0:1]
	v_or_b32_e32 v3, 16, v2
	v_lshl_add_u64 v[10:11], v[10:11], 0, v[8:9]
	global_load_dwordx4 v[22:25], v[6:7], off nt
	global_load_dwordx4 v[26:29], v[10:11], off nt
	v_mul_hi_i32_i24_e32 v7, s43, v3
	v_mul_i32_i24_e32 v6, s43, v3
	v_or_b32_e32 v3, 24, v2
	v_lshl_add_u64 v[6:7], v[6:7], 2, v[86:87]
	v_mul_hi_i32_i24_e32 v11, s43, v3
	v_mul_i32_i24_e32 v10, s43, v3
	v_lshl_add_u64 v[6:7], v[6:7], 0, s[0:1]
	v_lshl_add_u64 v[10:11], v[10:11], 2, v[86:87]
	v_lshl_add_u64 v[6:7], v[6:7], 0, v[8:9]
	v_lshl_add_u64 v[10:11], v[10:11], 0, s[0:1]
	v_or_b32_e32 v3, 32, v2
	v_lshl_add_u64 v[10:11], v[10:11], 0, v[8:9]
	global_load_dwordx4 v[30:33], v[6:7], off nt
	global_load_dwordx4 v[34:37], v[10:11], off nt
	v_mul_hi_i32_i24_e32 v7, s43, v3
	v_mul_i32_i24_e32 v6, s43, v3
	v_or_b32_e32 v3, 40, v2
	v_lshl_add_u64 v[6:7], v[6:7], 2, v[86:87]
	v_mul_hi_i32_i24_e32 v11, s43, v3
	v_mul_i32_i24_e32 v10, s43, v3
	v_lshl_add_u64 v[6:7], v[6:7], 0, s[0:1]
	v_lshl_add_u64 v[10:11], v[10:11], 2, v[86:87]
	v_lshl_add_u64 v[6:7], v[6:7], 0, v[8:9]
	v_lshl_add_u64 v[10:11], v[10:11], 0, s[0:1]
	v_or_b32_e32 v3, 48, v2
	v_lshl_add_u64 v[10:11], v[10:11], 0, v[8:9]
	global_load_dwordx4 v[38:41], v[6:7], off nt
	global_load_dwordx4 v[42:45], v[10:11], off nt
	v_mul_hi_i32_i24_e32 v7, s43, v3
	v_mul_i32_i24_e32 v6, s43, v3
	v_or_b32_e32 v3, 56, v2
	v_lshl_add_u64 v[6:7], v[6:7], 2, v[86:87]
	v_mul_hi_i32_i24_e32 v11, s43, v3
	v_mul_i32_i24_e32 v10, s43, v3
	v_lshl_add_u64 v[6:7], v[6:7], 0, s[0:1]
	v_lshl_add_u64 v[10:11], v[10:11], 2, v[86:87]
	v_lshl_add_u64 v[6:7], v[6:7], 0, v[8:9]
	v_lshl_add_u64 v[10:11], v[10:11], 0, s[0:1]
	v_lshl_add_u64 v[8:9], v[10:11], 0, v[8:9]
	global_load_dwordx4 v[46:49], v[6:7], off nt
	global_load_dwordx4 v[50:53], v[8:9], off nt
	v_ashrrev_i32_e32 v3, 31, v2
	s_cmp_lg_u64 s[6:7], 0
	s_cselect_b64 s[10:11], -1, 0
	s_cmp_eq_u64 s[6:7], 0
	v_lshl_add_u64 v[2:3], v[2:3], 2, s[6:7]
	s_cbranch_scc1 .LBB0_795
	global_load_dword v6, v[2:3], off nt
	global_load_dword v7, v[2:3], off offset:32 nt
	v_cndmask_b32_e64 v5, 0, 1, s[10:11]
	v_cmp_ne_u32_e64 s[0:1], 1, v5
	s_andn2_b64 vcc, exec, s[10:11]
	s_cbranch_vccnz .LBB0_796
.LBB0_660:
	global_load_dword v8, v[2:3], off offset:64 nt
	global_load_dword v9, v[2:3], off offset:96 nt
	s_cbranch_execnz .LBB0_662

; __device__ __forceinline__ void cvt_load(const CvtItem& c, const int lane, f32x4 (&vv)[8], float (&gv)[8]) {
;     ...
; #pragma unroll
;         for (int i = 0; i < 8; ++i) gv[i] = c.gain ? c.gain[c.k0 + 8 * i + kr] : 1.0f;
.LBB0_662:
	s_and_b64 vcc, exec, s[0:1]
	s_cbranch_vccnz .LBB0_797
	global_load_dword v10, v[2:3], off offset:128 nt
	global_load_dword v11, v[2:3], off offset:160 nt
	s_cbranch_execnz .LBB0_665

; __device__ __forceinline__ void cvt_load(const CvtItem& c, const int lane, f32x4 (&vv)[8], float (&gv)[8]) {
;     ...
; #pragma unroll
;         for (int i = 0; i < 8; ++i) gv[i] = c.gain ? c.gain[c.k0 + 8 * i + kr] : 1.0f;
.LBB0_665:
	s_and_b64 vcc, exec, s[0:1]
	s_cbranch_vccnz .LBB0_798
	global_load_dword v12, v[2:3], off offset:192 nt
	global_load_dword v13, v[2:3], off offset:224 nt
	s_cbranch_execnz .LBB0_668

; __device__ __forceinline__ CvtItem cvt_decode(const Args& A, const int it) {
;     ...
;     const int kb = r / nblk, nb = r % nblk; c.k0 = 64 * kb; c.n0 = 32 * nb; c.spec = (kind == 2) && (c.n0 >= 3072);
;     c.W = W0; c.col0 = c.n0;
;     if (kind == 0) { const int pn = c.n0 >> 8, bj = (c.n0 >> 7) & 1, jj = c.n0 & 127; c.W = bj ? W1 : W0; c.col0 = pn * 128 + jj; }
;     if (kind == 2) c.col0 = (c.n0 < 1024) ? c.n0 : c.n0 + 16;
;     return c;
; }
; __device__ __forceinline__ void cvt_load(const CvtItem& c, const int lane, f32x4 (&vv)[8], float (&gv)[8]) {
;     const int kr = lane >> 3, nq = lane & 7;
;     if (!c.spec) {
; #pragma unroll
;         for (int i = 0; i < 8; ++i) vv[i] = *(const f32x4*)(c.W + (size_t)(c.k0 + 8 * i + kr) * c.Nsrc + c.col0 + 4 * nq);
; #pragma unroll
;         for (int i = 0; i < 8; ++i) gv[i] = c.gain ? c.gain[c.k0 + 8 * i + kr] : 1.0f;
; __device__ __forceinline__ void convert_weights(const Args& A, LAS unsigned char* ldsl, int wave, int lane, const CvtList Lst, int gw, int NGW) {
;     ...
;         CvtItem nxt = cur; f32x4 vb[8]; float gb[8];
; #pragma unroll
;         for (int i = 0; i < 8; ++i) { vb[i] = va[i]; gb[i] = ga[i]; }
;         if (more) { nxt = cvt_decode(A, CVT_MAP(vn)); cvt_load(nxt, lane, vb, gb); }
.LBB0_693:
	s_sext_i32_i16 s0, s37
	v_cvt_f32_i32_e32 v18, s0
	s_sext_i32_i16 s1, s36
	v_cvt_f32_i32_e32 v19, s1
	s_xor_b32 s0, s1, s0
	v_rcp_iflag_f32_e32 v20, v18
	s_ashr_i32 s0, s0, 30
	s_or_b32 s12, s0, 1
	v_mov_b64_e32 v[56:57], v[24:25]
	v_mul_f32_e32 v20, v19, v20
	v_trunc_f32_e32 v20, v20
	v_fma_f32 v19, -v20, v18, v19
	v_cvt_i32_f32_e32 v20, v20
	v_cmp_ge_f32_e64 s[0:1], |v19|, |v18|
	s_and_b64 s[0:1], s[0:1], exec
	s_cselect_b32 s0, s12, 0
	v_readfirstlane_b32 s1, v20
	s_add_i32 s0, s1, s0
	s_sext_i32_i16 s1, s0
	s_mul_i32 s0, s0, s37
	s_sub_i32 s19, s36, s0
	s_sext_i32_i16 s0, s19
	s_lshl_b32 s18, s0, 5
	s_cmpk_gt_i32 s0, 0x5f
	s_cselect_b64 s[12:13], -1, 0
	s_bitcmp0_b32 s19, 2
	s_cselect_b64 vcc, -1, 0
	v_cndmask_b32_e32 v16, v16, v14, vcc
	v_cndmask_b32_e32 v17, v17, v15, vcc
	v_cndmask_b32_e64 v91, v15, v17, s[14:15]
	v_cndmask_b32_e64 v90, v14, v16, s[14:15]
	s_and_b64 s[12:13], s[16:17], s[12:13]
	v_mov_b64_e32 v[20:21], v[12:13]
	v_mov_b64_e32 v[60:61], v[28:29]
	v_mov_b64_e32 v[64:65], v[32:33]
	v_mov_b64_e32 v[68:69], v[36:37]
	v_mov_b64_e32 v[72:73], v[40:41]
	v_mov_b64_e32 v[76:77], v[44:45]
	v_mov_b64_e32 v[80:81], v[48:49]
	v_mov_b64_e32 v[84:85], v[52:53]
	s_lshl_b32 s19, s1, 6
	s_mov_b64 s[40:41], -1
	s_and_b64 vcc, exec, s[12:13]
	v_mov_b64_e32 v[18:19], v[10:11]
	v_mov_b64_e32 v[16:17], v[8:9]
	v_mov_b64_e32 v[14:15], v[6:7]
	v_mov_b64_e32 v[54:55], v[22:23]
	v_mov_b64_e32 v[58:59], v[26:27]
	v_mov_b64_e32 v[62:63], v[30:31]
	v_mov_b64_e32 v[66:67], v[34:35]
	v_mov_b64_e32 v[70:71], v[38:39]
	v_mov_b64_e32 v[74:75], v[42:43]
	v_mov_b64_e32 v[78:79], v[46:47]
	v_mov_b64_e32 v[82:83], v[50:51]
	s_cbranch_vccnz .LBB0_707
	s_or_b32 s1, s18, 16
	s_cmp_lt_i32 s0, 32
	s_cselect_b32 s12, s18, s1
	s_lshl_b32 s0, s0, 4
	s_and_b32 s0, s0, 0xffffff80
	s_and_b32 s1, s18, 0x60
	s_or_b32 s13, s0, s1
	s_and_b64 s[0:1], s[14:15], exec
	s_cselect_b32 s13, s13, s18
	s_and_b64 s[0:1], s[16:17], exec
	s_cselect_b32 s0, s12, s13
	v_or_b32_e32 v14, s19, v96
	v_mul_hi_i32_i24_e32 v17, s47, v14
	v_mul_i32_i24_e32 v16, s47, v14
	s_ashr_i32 s1, s0, 31
	v_or_b32_e32 v15, 8, v14
	v_lshl_add_u64 v[16:17], v[16:17], 2, v[90:91]
	s_lshl_b64 s[0:1], s[0:1], 2
	v_mul_hi_i32_i24_e32 v19, s47, v15
	v_mul_i32_i24_e32 v18, s47, v15
	v_lshl_add_u64 v[16:17], v[16:17], 0, s[0:1]
	v_lshl_add_u64 v[18:19], v[18:19], 2, v[90:91]
	v_lshl_add_u64 v[16:17], v[16:17], 0, v[2:3]
	v_lshl_add_u64 v[18:19], v[18:19], 0, s[0:1]
	v_or_b32_e32 v15, 16, v14
	v_lshl_add_u64 v[18:19], v[18:19], 0, v[2:3]
	global_load_dwordx4 v[54:57], v[16:17], off nt
	global_load_dwordx4 v[58:61], v[18:19], off nt
	v_mul_hi_i32_i24_e32 v17, s47, v15
	v_mul_i32_i24_e32 v16, s47, v15
	v_or_b32_e32 v15, 24, v14
	v_lshl_add_u64 v[16:17], v[16:17], 2, v[90:91]
	v_mul_hi_i32_i24_e32 v19, s47, v15
	v_mul_i32_i24_e32 v18, s47, v15
	v_lshl_add_u64 v[16:17], v[16:17], 0, s[0:1]
	v_lshl_add_u64 v[18:19], v[18:19], 2, v[90:91]
	v_lshl_add_u64 v[16:17], v[16:17], 0, v[2:3]
	v_lshl_add_u64 v[18:19], v[18:19], 0, s[0:1]
	v_or_b32_e32 v15, 32, v14
	v_lshl_add_u64 v[18:19], v[18:19], 0, v[2:3]
	global_load_dwordx4 v[62:65], v[16:17], off nt
	global_load_dwordx4 v[66:69], v[18:19], off nt
	v_mul_hi_i32_i24_e32 v17, s47, v15
	v_mul_i32_i24_e32 v16, s47, v15
	v_or_b32_e32 v15, 40, v14
	v_lshl_add_u64 v[16:17], v[16:17], 2, v[90:91]
	v_mul_hi_i32_i24_e32 v19, s47, v15
	v_mul_i32_i24_e32 v18, s47, v15
	v_lshl_add_u64 v[16:17], v[16:17], 0, s[0:1]
	v_lshl_add_u64 v[18:19], v[18:19], 2, v[90:91]
	v_lshl_add_u64 v[16:17], v[16:17], 0, v[2:3]
	v_lshl_add_u64 v[18:19], v[18:19], 0, s[0:1]
	v_or_b32_e32 v15, 48, v14
	v_lshl_add_u64 v[18:19], v[18:19], 0, v[2:3]
	global_load_dwordx4 v[70:73], v[16:17], off nt
	global_load_dwordx4 v[74:77], v[18:19], off nt
	v_mul_hi_i32_i24_e32 v17, s47, v15
	v_mul_i32_i24_e32 v16, s47, v15
	v_or_b32_e32 v15, 56, v14
	v_lshl_add_u64 v[16:17], v[16:17], 2, v[90:91]
	v_mul_hi_i32_i24_e32 v19, s47, v15
	v_mul_i32_i24_e32 v18, s47, v15
	v_lshl_add_u64 v[16:17], v[16:17], 0, s[0:1]
	v_lshl_add_u64 v[18:19], v[18:19], 2, v[90:91]
	v_lshl_add_u64 v[16:17], v[16:17], 0, v[2:3]
	v_lshl_add_u64 v[18:19], v[18:19], 0, s[0:1]
	v_lshl_add_u64 v[18:19], v[18:19], 0, v[2:3]
	global_load_dwordx4 v[78:81], v[16:17], off nt
	global_load_dwordx4 v[82:85], v[18:19], off nt
	v_ashrrev_i32_e32 v15, 31, v14
	s_cmp_lg_u64 s[38:39], 0
	s_cselect_b64 s[12:13], -1, 0
	s_cmp_eq_u64 s[38:39], 0
	v_lshl_add_u64 v[92:93], v[14:15], 2, s[38:39]
	s_cbranch_scc1 .LBB0_777
	global_load_dword v14, v[92:93], off nt
	global_load_dword v15, v[92:93], off offset:32 nt
	s_cbranch_execnz .LBB0_697

; __device__ __forceinline__ void cvt_load(const CvtItem& c, const int lane, f32x4 (&vv)[8], float (&gv)[8]) {
;     ...
; #pragma unroll
;         for (int i = 0; i < 8; ++i) gv[i] = c.gain ? c.gain[c.k0 + 8 * i + kr] : 1.0f;
.LBB0_697:
	v_cndmask_b32_e64 v16, 0, 1, s[12:13]
	v_cmp_ne_u32_e64 s[0:1], 1, v16
	s_andn2_b64 vcc, exec, s[12:13]
	s_cbranch_vccnz .LBB0_778
	global_load_dword v16, v[92:93], off offset:64 nt
	global_load_dword v17, v[92:93], off offset:96 nt
	s_cbranch_execnz .LBB0_700

; __device__ __forceinline__ void cvt_load(const CvtItem& c, const int lane, f32x4 (&vv)[8], float (&gv)[8]) {
;     ...
; #pragma unroll
;         for (int i = 0; i < 8; ++i) gv[i] = c.gain ? c.gain[c.k0 + 8 * i + kr] : 1.0f;
.LBB0_700:
	s_and_b64 vcc, exec, s[0:1]
	s_cbranch_vccnz .LBB0_779
	global_load_dword v18, v[92:93], off offset:128 nt
	global_load_dword v19, v[92:93], off offset:160 nt
	s_cbranch_execnz .LBB0_703

; __device__ __forceinline__ void cvt_load(const CvtItem& c, const int lane, f32x4 (&vv)[8], float (&gv)[8]) {
;     ...
; #pragma unroll
;         for (int i = 0; i < 8; ++i) gv[i] = c.gain ? c.gain[c.k0 + 8 * i + kr] : 1.0f;
.LBB0_703:
	s_and_b64 vcc, exec, s[0:1]
	s_cbranch_vccnz .LBB0_780
	global_load_dword v20, v[92:93], off offset:192 nt
	global_load_dword v21, v[92:93], off offset:224 nt
	s_cbranch_execnz .LBB0_706

; __device__ __forceinline__ void cvt_finish(const CvtItem& c, const int lane, LAS float* scr, const f32x4 (&vv)[8], const float (&gv)[8]) {
;     if (c.spec) {
;         const int np = c.n0 + (lane & 31);
;         int col = 0; bool valid = true;
;         if (np < 3088) col = 1024 + (np - 3072); else if (np < NIN) col = np; else valid = false;
;         float ev[32];
; #pragma unroll
;         for (int i = 0; i < 32; ++i) ev[i] = c.W[(size_t)(c.k0 + 2 * i + (lane >> 5)) * c.Nsrc + col];
.LBB0_709:
	s_andn2_b64 vcc, exec, s[0:1]
	s_cbranch_vccnz .LBB0_775
	v_add_u32_e32 v89, s45, v99
	s_movk_i32 s0, 0xc10
	s_movk_i32 s12, 0xc14
	v_cmp_gt_i32_e32 vcc, s0, v89
	v_cmp_gt_u32_e64 s[0:1], s12, v89
	v_add_u32_e32 v92, 0xfffff800, v89
	s_cmp_lg_u64 s[6:7], 0
	v_cndmask_b32_e64 v93, 0, v89, s[0:1]
	v_cndmask_b32_e32 v94, v93, v92, vcc
	v_add_u32_e32 v92, s20, v100
	v_mad_u64_u32 v[108:109], s[0:1], v92, s43, 0
	v_ashrrev_i32_e32 v93, 31, v92
	v_mov_b32_e32 v110, v109
	v_ashrrev_i32_e32 v95, 31, v94
	v_mad_u64_u32 v[110:111], s[0:1], v93, s43, v[110:111]
	v_lshl_add_u64 v[94:95], v[94:95], 2, v[86:87]
	v_mov_b32_e32 v109, v110
	v_lshl_add_u64 v[108:109], v[108:109], 2, v[94:95]
	global_load_dword v113, v[108:109], off nt
	v_add_u32_e32 v107, 2, v92
	v_mad_u64_u32 v[108:109], s[0:1], v107, s43, 0
	v_ashrrev_i32_e32 v111, 31, v107
	v_mov_b32_e32 v110, v109
	v_mad_u64_u32 v[110:111], s[0:1], v111, s43, v[110:111]
	v_mov_b32_e32 v109, v110
	v_lshl_add_u64 v[108:109], v[108:109], 2, v[94:95]
	global_load_dword v107, v[108:109], off nt
	v_add_u32_e32 v108, 4, v92
	v_ashrrev_i32_e32 v111, 31, v108
	v_mad_u64_u32 v[108:109], s[0:1], v108, s43, 0
	v_mov_b32_e32 v110, v109
	v_mad_u64_u32 v[110:111], s[0:1], v111, s43, v[110:111]
	v_mov_b32_e32 v109, v110
	v_lshl_add_u64 v[108:109], v[108:109], 2, v[94:95]
	global_load_dword v108, v[108:109], off nt
	v_add_u32_e32 v109, 6, v92
	v_mad_u64_u32 v[110:111], s[0:1], v109, s43, 0
	v_ashrrev_i32_e32 v114, 31, v109
	v_mov_b32_e32 v112, v111
	s_waitcnt vmcnt(2)
	v_mad_u64_u32 v[114:115], s[0:1], v114, s43, v[112:113]
	v_mov_b32_e32 v111, v114
	v_lshl_add_u64 v[110:111], v[110:111], 2, v[94:95]
	global_load_dword v109, v[110:111], off nt
	v_add_u32_e32 v110, 8, v92
	v_ashrrev_i32_e32 v114, 31, v110
	v_mad_u64_u32 v[110:111], s[0:1], v110, s43, 0
	v_mov_b32_e32 v112, v111
	v_mad_u64_u32 v[114:115], s[0:1], v114, s43, v[112:113]
	v_mov_b32_e32 v111, v114
	v_lshl_add_u64 v[110:111], v[110:111], 2, v[94:95]
	global_load_dword v110, v[110:111], off nt
	v_add_u32_e32 v111, 10, v92
	v_mad_u64_u32 v[114:115], s[0:1], v111, s43, 0
	v_ashrrev_i32_e32 v116, 31, v111
	v_mov_b32_e32 v112, v115
	v_mad_u64_u32 v[116:117], s[0:1], v116, s43, v[112:113]
	v_mov_b32_e32 v115, v116
	v_lshl_add_u64 v[114:115], v[114:115], 2, v[94:95]
	v_add_u32_e32 v112, 12, v92
	global_load_dword v111, v[114:115], off nt
	v_mad_u64_u32 v[114:115], s[0:1], v112, s43, 0
	v_ashrrev_i32_e32 v116, 31, v112
	v_mov_b32_e32 v112, v115
	v_mad_u64_u32 v[116:117], s[0:1], v116, s43, v[112:113]
	v_mov_b32_e32 v115, v116
	v_lshl_add_u64 v[114:115], v[114:115], 2, v[94:95]
	global_load_dword v112, v[114:115], off nt
	v_add_u32_e32 v114, 14, v92
	v_ashrrev_i32_e32 v117, 31, v114
	v_mad_u64_u32 v[114:115], s[0:1], v114, s43, 0
	v_mov_b32_e32 v116, v115
	v_mad_u64_u32 v[116:117], s[0:1], v117, s43, v[116:117]
	v_mov_b32_e32 v115, v116
	v_lshl_add_u64 v[114:115], v[114:115], 2, v[94:95]
	global_load_dword v121, v[114:115], off nt
	v_add_u32_e32 v114, 16, v92
	v_ashrrev_i32_e32 v117, 31, v114
	v_mad_u64_u32 v[114:115], s[0:1], v114, s43, 0
	v_mov_b32_e32 v116, v115
	v_mad_u64_u32 v[116:117], s[0:1], v117, s43, v[116:117]
	v_mov_b32_e32 v115, v116
	v_lshl_add_u64 v[114:115], v[114:115], 2, v[94:95]
	global_load_dword v114, v[114:115], off nt
	v_add_u32_e32 v115, 18, v92
	v_mad_u64_u32 v[116:117], s[0:1], v115, s43, 0
	v_ashrrev_i32_e32 v119, 31, v115
	v_mov_b32_e32 v118, v117
	v_mad_u64_u32 v[118:119], s[0:1], v119, s43, v[118:119]
	v_mov_b32_e32 v117, v118
	v_lshl_add_u64 v[116:117], v[116:117], 2, v[94:95]
	global_load_dword v115, v[116:117], off nt
	v_add_u32_e32 v116, 20, v92
	v_ashrrev_i32_e32 v119, 31, v116
	v_mad_u64_u32 v[116:117], s[0:1], v116, s43, 0
	v_mov_b32_e32 v118, v117
	v_mad_u64_u32 v[118:119], s[0:1], v119, s43, v[118:119]
	v_mov_b32_e32 v117, v118
	v_lshl_add_u64 v[116:117], v[116:117], 2, v[94:95]
	global_load_dword v116, v[116:117], off nt
	v_add_u32_e32 v117, 22, v92
	v_mad_u64_u32 v[118:119], s[0:1], v117, s43, 0
	v_ashrrev_i32_e32 v122, 31, v117
	v_mov_b32_e32 v120, v119
	s_waitcnt vmcnt(3)
	v_mad_u64_u32 v[122:123], s[0:1], v122, s43, v[120:121]
	v_mov_b32_e32 v119, v122
	v_lshl_add_u64 v[118:119], v[118:119], 2, v[94:95]
	global_load_dword v117, v[118:119], off nt
	v_add_u32_e32 v118, 24, v92
	v_ashrrev_i32_e32 v122, 31, v118
	v_mad_u64_u32 v[118:119], s[0:1], v118, s43, 0
	v_mov_b32_e32 v120, v119
	v_mad_u64_u32 v[122:123], s[0:1], v122, s43, v[120:121]
	v_mov_b32_e32 v119, v122
	v_lshl_add_u64 v[118:119], v[118:119], 2, v[94:95]
	global_load_dword v118, v[118:119], off nt
	v_add_u32_e32 v119, 26, v92
	v_mad_u64_u32 v[122:123], s[0:1], v119, s43, 0
	v_ashrrev_i32_e32 v124, 31, v119
	v_mov_b32_e32 v120, v123
	v_mad_u64_u32 v[124:125], s[0:1], v124, s43, v[120:121]
	v_mov_b32_e32 v123, v124
	v_lshl_add_u64 v[122:123], v[122:123], 2, v[94:95]
	v_add_u32_e32 v120, 28, v92
	global_load_dword v119, v[122:123], off nt
	v_mad_u64_u32 v[122:123], s[0:1], v120, s43, 0
	v_ashrrev_i32_e32 v124, 31, v120
	v_mov_b32_e32 v120, v123
	v_mad_u64_u32 v[124:125], s[0:1], v124, s43, v[120:121]
	v_mov_b32_e32 v123, v124
	v_lshl_add_u64 v[122:123], v[122:123], 2, v[94:95]
	global_load_dword v120, v[122:123], off nt
	v_add_u32_e32 v122, 30, v92
	v_ashrrev_i32_e32 v125, 31, v122
	v_mad_u64_u32 v[122:123], s[0:1], v122, s43, 0
	v_mov_b32_e32 v124, v123
	v_mad_u64_u32 v[124:125], s[0:1], v125, s43, v[124:125]
	v_mov_b32_e32 v123, v124
	v_lshl_add_u64 v[122:123], v[122:123], 2, v[94:95]
	global_load_dword v129, v[122:123], off nt
	v_add_u32_e32 v122, 32, v92
	v_ashrrev_i32_e32 v125, 31, v122
	v_mad_u64_u32 v[122:123], s[0:1], v122, s43, 0
	v_mov_b32_e32 v124, v123
	v_mad_u64_u32 v[124:125], s[0:1], v125, s43, v[124:125]
	v_mov_b32_e32 v123, v124
	v_lshl_add_u64 v[122:123], v[122:123], 2, v[94:95]
	global_load_dword v122, v[122:123], off nt
	v_add_u32_e32 v123, 34, v92
	v_mad_u64_u32 v[124:125], s[0:1], v123, s43, 0
	v_ashrrev_i32_e32 v127, 31, v123
	v_mov_b32_e32 v126, v125
	v_mad_u64_u32 v[126:127], s[0:1], v127, s43, v[126:127]
	v_mov_b32_e32 v125, v126
	v_lshl_add_u64 v[124:125], v[124:125], 2, v[94:95]
	global_load_dword v123, v[124:125], off nt
	v_add_u32_e32 v124, 36, v92
	v_ashrrev_i32_e32 v127, 31, v124
	v_mad_u64_u32 v[124:125], s[0:1], v124, s43, 0
	v_mov_b32_e32 v126, v125
	v_mad_u64_u32 v[126:127], s[0:1], v127, s43, v[126:127]
	v_mov_b32_e32 v125, v126
	v_lshl_add_u64 v[124:125], v[124:125], 2, v[94:95]
	global_load_dword v124, v[124:125], off nt
	v_add_u32_e32 v125, 38, v92
	v_mad_u64_u32 v[126:127], s[0:1], v125, s43, 0
	v_ashrrev_i32_e32 v130, 31, v125
	v_mov_b32_e32 v128, v127
	s_waitcnt vmcnt(3)
; __device__ __forceinline__ void cvt_finish(const CvtItem& c, const int lane, LAS float* scr, const f32x4 (&vv)[8], const float (&gv)[8]) {
;     if (c.spec) {
;         const int np = c.n0 + (lane & 31);
;         int col = 0; bool valid = true;
;         if (np < 3088) col = 1024 + (np - 3072); else if (np < NIN) col = np; else valid = false;
;         float ev[32];
; #pragma unroll
;         for (int i = 0; i < 32; ++i) ev[i] = c.W[(size_t)(c.k0 + 2 * i + (lane >> 5)) * c.Nsrc + col];
; #pragma unroll
;         for (int i = 0; i < 32; ++i) { const int kk = 2 * i + (lane >> 5); float v = valid ? ev[i] : 0.f; if (c.gain) v *= c.gain[c.k0 + kk]; scr[kk * 33 + (lane & 31)] = v; }
	v_mad_u64_u32 v[130:131], s[0:1], v130, s43, v[128:129]
	v_mov_b32_e32 v127, v130
	v_lshl_add_u64 v[126:127], v[126:127], 2, v[94:95]
	global_load_dword v125, v[126:127], off nt
	v_add_u32_e32 v126, 40, v92
	v_ashrrev_i32_e32 v130, 31, v126
	v_mad_u64_u32 v[126:127], s[0:1], v126, s43, 0
	v_mov_b32_e32 v128, v127
	v_mad_u64_u32 v[130:131], s[0:1], v130, s43, v[128:129]
	v_mov_b32_e32 v127, v130
	v_lshl_add_u64 v[126:127], v[126:127], 2, v[94:95]
	global_load_dword v126, v[126:127], off nt
	v_add_u32_e32 v127, 42, v92
	v_mad_u64_u32 v[130:131], s[0:1], v127, s43, 0
	v_ashrrev_i32_e32 v132, 31, v127
	v_mov_b32_e32 v128, v131
	v_mad_u64_u32 v[132:133], s[0:1], v132, s43, v[128:129]
	v_mov_b32_e32 v131, v132
	v_lshl_add_u64 v[130:131], v[130:131], 2, v[94:95]
	v_add_u32_e32 v128, 44, v92
	global_load_dword v127, v[130:131], off nt
	v_mad_u64_u32 v[130:131], s[0:1], v128, s43, 0
	v_ashrrev_i32_e32 v132, 31, v128
	v_mov_b32_e32 v128, v131
	v_mad_u64_u32 v[132:133], s[0:1], v132, s43, v[128:129]
	v_mov_b32_e32 v131, v132
	v_lshl_add_u64 v[130:131], v[130:131], 2, v[94:95]
	global_load_dword v128, v[130:131], off nt
	v_add_u32_e32 v130, 46, v92
	v_ashrrev_i32_e32 v133, 31, v130
	v_mad_u64_u32 v[130:131], s[0:1], v130, s43, 0
	v_mov_b32_e32 v132, v131
	v_mad_u64_u32 v[132:133], s[0:1], v133, s43, v[132:133]
	v_mov_b32_e32 v131, v132
	v_lshl_add_u64 v[130:131], v[130:131], 2, v[94:95]
	global_load_dword v137, v[130:131], off nt
	v_add_u32_e32 v130, 48, v92
	v_ashrrev_i32_e32 v133, 31, v130
	v_mad_u64_u32 v[130:131], s[0:1], v130, s43, 0
	v_mov_b32_e32 v132, v131
	v_mad_u64_u32 v[132:133], s[0:1], v133, s43, v[132:133]
	v_mov_b32_e32 v131, v132
	v_lshl_add_u64 v[130:131], v[130:131], 2, v[94:95]
	global_load_dword v130, v[130:131], off nt
	v_add_u32_e32 v131, 50, v92
	v_mad_u64_u32 v[132:133], s[0:1], v131, s43, 0
	v_ashrrev_i32_e32 v135, 31, v131
	v_mov_b32_e32 v134, v133
	v_mad_u64_u32 v[134:135], s[0:1], v135, s43, v[134:135]
	v_mov_b32_e32 v133, v134
	v_lshl_add_u64 v[132:133], v[132:133], 2, v[94:95]
	global_load_dword v131, v[132:133], off nt
	v_add_u32_e32 v132, 52, v92
	v_ashrrev_i32_e32 v135, 31, v132
	v_mad_u64_u32 v[132:133], s[0:1], v132, s43, 0
	v_mov_b32_e32 v134, v133
	v_mad_u64_u32 v[134:135], s[0:1], v135, s43, v[134:135]
	v_mov_b32_e32 v133, v134
	v_lshl_add_u64 v[132:133], v[132:133], 2, v[94:95]
	global_load_dword v132, v[132:133], off nt
	v_add_u32_e32 v133, 54, v92
	v_mad_u64_u32 v[134:135], s[0:1], v133, s43, 0
	v_ashrrev_i32_e32 v138, 31, v133
	v_mov_b32_e32 v136, v135
	s_waitcnt vmcnt(3)
	v_mad_u64_u32 v[138:139], s[0:1], v138, s43, v[136:137]
	v_mov_b32_e32 v135, v138
	v_lshl_add_u64 v[134:135], v[134:135], 2, v[94:95]
	global_load_dword v133, v[134:135], off nt
	v_add_u32_e32 v134, 56, v92
	v_ashrrev_i32_e32 v138, 31, v134
	v_mad_u64_u32 v[134:135], s[0:1], v134, s43, 0
	v_mov_b32_e32 v136, v135
	v_mad_u64_u32 v[138:139], s[0:1], v138, s43, v[136:137]
	v_mov_b32_e32 v135, v138
	v_lshl_add_u64 v[134:135], v[134:135], 2, v[94:95]
	global_load_dword v134, v[134:135], off nt
	v_add_u32_e32 v135, 58, v92
	v_mad_u64_u32 v[138:139], s[0:1], v135, s43, 0
	v_ashrrev_i32_e32 v140, 31, v135
	v_mov_b32_e32 v136, v139
	v_mad_u64_u32 v[140:141], s[0:1], v140, s43, v[136:137]
	v_mov_b32_e32 v139, v140
	v_lshl_add_u64 v[138:139], v[138:139], 2, v[94:95]
	v_add_u32_e32 v136, 60, v92
	global_load_dword v135, v[138:139], off nt
	v_mad_u64_u32 v[138:139], s[0:1], v136, s43, 0
	v_ashrrev_i32_e32 v140, 31, v136
	v_mov_b32_e32 v136, v139
	v_mad_u64_u32 v[140:141], s[0:1], v140, s43, v[136:137]
	v_mov_b32_e32 v139, v140
	v_lshl_add_u64 v[138:139], v[138:139], 2, v[94:95]
	global_load_dword v136, v[138:139], off nt
	v_add_u32_e32 v138, 62, v92
	v_ashrrev_i32_e32 v141, 31, v138
	v_mad_u64_u32 v[138:139], s[0:1], v138, s43, 0
	v_mov_b32_e32 v140, v139
	v_mad_u64_u32 v[140:141], s[0:1], v141, s43, v[140:141]
	v_mov_b32_e32 v139, v140
	v_lshl_add_u64 v[94:95], v[138:139], 2, v[94:95]
	global_load_dword v94, v[94:95], off nt
	v_cmp_gt_i32_e64 s[0:1], s12, v89
	s_cselect_b64 s[12:13], -1, 0
	s_cmp_eq_u64 s[6:7], 0
	v_cndmask_b32_e64 v89, 0, v113, s[0:1]
	v_lshl_add_u64 v[92:93], v[92:93], 2, s[6:7]
	s_cbranch_scc1 .LBB0_712
	global_load_dword v95, v[92:93], off nt
	s_waitcnt vmcnt(0)
	v_mul_f32_e32 v89, v89, v95
.LBB0_712:
	ds_write_b32 v106, v89
	v_cndmask_b32_e64 v89, 0, 1, s[12:13]
	v_cmp_ne_u32_e64 s[36:37], 1, v89
	s_andn2_b64 vcc, exec, s[12:13]
	v_cndmask_b32_e64 v89, 0, v107, s[0:1]
	s_cbranch_vccnz .LBB0_714
	global_load_dword v95, v[92:93], off offset:8 nt
	s_waitcnt vmcnt(0)
	v_mul_f32_e32 v89, v89, v95
.LBB0_714:
	ds_write_b32 v106, v89 offset:264
	s_and_b64 vcc, exec, s[36:37]
	v_cndmask_b32_e64 v89, 0, v108, s[0:1]
	s_cbranch_vccnz .LBB0_716
	global_load_dword v95, v[92:93], off offset:16 nt
	s_waitcnt vmcnt(0)
	v_mul_f32_e32 v89, v89, v95
.LBB0_716:
	ds_write_b32 v106, v89 offset:528
	s_and_b64 vcc, exec, s[36:37]
	v_cndmask_b32_e64 v89, 0, v109, s[0:1]
	s_cbranch_vccnz .LBB0_718
	global_load_dword v95, v[92:93], off offset:24 nt
	s_waitcnt vmcnt(0)
	v_mul_f32_e32 v89, v89, v95
.LBB0_718:
	ds_write_b32 v106, v89 offset:792
	s_and_b64 vcc, exec, s[36:37]
	v_cndmask_b32_e64 v89, 0, v110, s[0:1]
	s_cbranch_vccnz .LBB0_720
	global_load_dword v95, v[92:93], off offset:32 nt
	s_waitcnt vmcnt(0)
	v_mul_f32_e32 v89, v89, v95
.LBB0_720:
	ds_write_b32 v106, v89 offset:1056
	s_and_b64 vcc, exec, s[36:37]
	v_cndmask_b32_e64 v89, 0, v111, s[0:1]
	s_cbranch_vccnz .LBB0_722
	global_load_dword v95, v[92:93], off offset:40 nt
	s_waitcnt vmcnt(0)
	v_mul_f32_e32 v89, v89, v95
; __device__ __forceinline__ void cvt_finish(const CvtItem& c, const int lane, LAS float* scr, const f32x4 (&vv)[8], const float (&gv)[8]) {
;     ...
;         for (int i = 0; i < 32; ++i) { const int kk = 2 * i + (lane >> 5); float v = valid ? ev[i] : 0.f; if (c.gain) v *= c.gain[c.k0 + kk]; scr[kk * 33 + (lane & 31)] = v; }
.LBB0_722:
	ds_write_b32 v106, v89 offset:1320
	s_and_b64 vcc, exec, s[36:37]
	v_cndmask_b32_e64 v89, 0, v112, s[0:1]
	s_cbranch_vccnz .LBB0_724
	global_load_dword v95, v[92:93], off offset:48 nt
	s_waitcnt vmcnt(0)
	v_mul_f32_e32 v89, v89, v95
.LBB0_724:
	ds_write_b32 v106, v89 offset:1584
	s_and_b64 vcc, exec, s[36:37]
	v_cndmask_b32_e64 v89, 0, v121, s[0:1]
	s_cbranch_vccnz .LBB0_726
	global_load_dword v95, v[92:93], off offset:56 nt
	s_waitcnt vmcnt(0)
	v_mul_f32_e32 v89, v89, v95
.LBB0_726:
	ds_write_b32 v106, v89 offset:1848
	s_and_b64 vcc, exec, s[36:37]
	v_cndmask_b32_e64 v89, 0, v114, s[0:1]
	s_cbranch_vccnz .LBB0_728
	global_load_dword v95, v[92:93], off offset:64 nt
	s_waitcnt vmcnt(0)
	v_mul_f32_e32 v89, v89, v95
.LBB0_728:
	ds_write_b32 v106, v89 offset:2112
	s_and_b64 vcc, exec, s[36:37]
	v_cndmask_b32_e64 v89, 0, v115, s[0:1]
	s_cbranch_vccnz .LBB0_730
	global_load_dword v95, v[92:93], off offset:72 nt
	s_waitcnt vmcnt(0)
	v_mul_f32_e32 v89, v89, v95
.LBB0_730:
	ds_write_b32 v106, v89 offset:2376
	s_and_b64 vcc, exec, s[36:37]
	v_cndmask_b32_e64 v89, 0, v116, s[0:1]
	s_cbranch_vccnz .LBB0_732
	global_load_dword v95, v[92:93], off offset:80 nt
	s_waitcnt vmcnt(0)
	v_mul_f32_e32 v89, v89, v95
.LBB0_732:
	ds_write_b32 v106, v89 offset:2640
	s_and_b64 vcc, exec, s[36:37]
	v_cndmask_b32_e64 v89, 0, v117, s[0:1]
	s_cbranch_vccnz .LBB0_734
	global_load_dword v95, v[92:93], off offset:88 nt
	s_waitcnt vmcnt(0)
	v_mul_f32_e32 v89, v89, v95
.LBB0_734:
	ds_write_b32 v106, v89 offset:2904
	s_and_b64 vcc, exec, s[36:37]
	v_cndmask_b32_e64 v89, 0, v118, s[0:1]
	s_cbranch_vccnz .LBB0_736
	global_load_dword v95, v[92:93], off offset:96 nt
	s_waitcnt vmcnt(0)
	v_mul_f32_e32 v89, v89, v95
.LBB0_736:
	ds_write_b32 v106, v89 offset:3168
	s_and_b64 vcc, exec, s[36:37]
	v_cndmask_b32_e64 v89, 0, v119, s[0:1]
	s_cbranch_vccnz .LBB0_738
	global_load_dword v95, v[92:93], off offset:104 nt
	s_waitcnt vmcnt(0)
	v_mul_f32_e32 v89, v89, v95
.LBB0_738:
	ds_write_b32 v106, v89 offset:3432
	s_and_b64 vcc, exec, s[36:37]
	v_cndmask_b32_e64 v89, 0, v120, s[0:1]
	s_cbranch_vccnz .LBB0_740
	global_load_dword v95, v[92:93], off offset:112 nt
	s_waitcnt vmcnt(0)
	v_mul_f32_e32 v89, v89, v95
.LBB0_740:
	ds_write_b32 v106, v89 offset:3696
	s_and_b64 vcc, exec, s[36:37]
	v_cndmask_b32_e64 v89, 0, v129, s[0:1]
	s_cbranch_vccnz .LBB0_742
	global_load_dword v95, v[92:93], off offset:120 nt
	s_waitcnt vmcnt(0)
	v_mul_f32_e32 v89, v89, v95
.LBB0_742:
	ds_write_b32 v106, v89 offset:3960
	s_and_b64 vcc, exec, s[36:37]
	v_cndmask_b32_e64 v89, 0, v122, s[0:1]
	s_cbranch_vccnz .LBB0_744
	global_load_dword v95, v[92:93], off offset:128 nt
	s_waitcnt vmcnt(0)
	v_mul_f32_e32 v89, v89, v95
.LBB0_744:
	ds_write_b32 v106, v89 offset:4224
	s_and_b64 vcc, exec, s[36:37]
	v_cndmask_b32_e64 v89, 0, v123, s[0:1]
	s_cbranch_vccnz .LBB0_746
	global_load_dword v95, v[92:93], off offset:136 nt
	s_waitcnt vmcnt(0)
	v_mul_f32_e32 v89, v89, v95
.LBB0_746:
	ds_write_b32 v106, v89 offset:4488
	s_and_b64 vcc, exec, s[36:37]
	v_cndmask_b32_e64 v89, 0, v124, s[0:1]
	s_cbranch_vccnz .LBB0_748
	global_load_dword v95, v[92:93], off offset:144 nt
	s_waitcnt vmcnt(0)
	v_mul_f32_e32 v89, v89, v95
.LBB0_748:
	ds_write_b32 v106, v89 offset:4752
	s_and_b64 vcc, exec, s[36:37]
	v_cndmask_b32_e64 v89, 0, v125, s[0:1]
	s_cbranch_vccnz .LBB0_750
	global_load_dword v95, v[92:93], off offset:152 nt
	s_waitcnt vmcnt(0)
	v_mul_f32_e32 v89, v89, v95
.LBB0_750:
	ds_write_b32 v106, v89 offset:5016
	s_and_b64 vcc, exec, s[36:37]
	v_cndmask_b32_e64 v89, 0, v126, s[0:1]
	s_cbranch_vccnz .LBB0_752
	global_load_dword v95, v[92:93], off offset:160 nt
	s_waitcnt vmcnt(0)
	v_mul_f32_e32 v89, v89, v95
.LBB0_752:
	ds_write_b32 v106, v89 offset:5280
	s_and_b64 vcc, exec, s[36:37]
	v_cndmask_b32_e64 v89, 0, v127, s[0:1]
	s_cbranch_vccnz .LBB0_754
	global_load_dword v95, v[92:93], off offset:168 nt
	s_waitcnt vmcnt(0)
	v_mul_f32_e32 v89, v89, v95
.LBB0_754:
	ds_write_b32 v106, v89 offset:5544
	s_and_b64 vcc, exec, s[36:37]
	v_cndmask_b32_e64 v89, 0, v128, s[0:1]
	s_cbranch_vccnz .LBB0_756
	global_load_dword v95, v[92:93], off offset:176 nt
	s_waitcnt vmcnt(0)
	v_mul_f32_e32 v89, v89, v95
.LBB0_756:
	ds_write_b32 v106, v89 offset:5808
	s_and_b64 vcc, exec, s[36:37]
	v_cndmask_b32_e64 v89, 0, v137, s[0:1]
	s_cbranch_vccnz .LBB0_758
	global_load_dword v95, v[92:93], off offset:184 nt
	s_waitcnt vmcnt(0)
	v_mul_f32_e32 v89, v89, v95
.LBB0_758:
	ds_write_b32 v106, v89 offset:6072
	s_and_b64 vcc, exec, s[36:37]
	s_waitcnt vmcnt(7)
	v_cndmask_b32_e64 v89, 0, v130, s[0:1]
	s_cbranch_vccnz .LBB0_760
	global_load_dword v95, v[92:93], off offset:192 nt
	s_waitcnt vmcnt(0)
	v_mul_f32_e32 v89, v89, v95
.LBB0_760:
	ds_write_b32 v106, v89 offset:6336
	s_and_b64 vcc, exec, s[36:37]
	s_waitcnt vmcnt(6)
	v_cndmask_b32_e64 v89, 0, v131, s[0:1]
	s_cbranch_vccnz .LBB0_762
	global_load_dword v95, v[92:93], off offset:200 nt
	s_waitcnt vmcnt(0)
	v_mul_f32_e32 v89, v89, v95
.LBB0_762:
	ds_write_b32 v106, v89 offset:6600
	s_and_b64 vcc, exec, s[36:37]
	s_waitcnt vmcnt(5)
	v_cndmask_b32_e64 v89, 0, v132, s[0:1]
	s_cbranch_vccnz .LBB0_764
	global_load_dword v95, v[92:93], off offset:208 nt
	s_waitcnt vmcnt(0)
	v_mul_f32_e32 v89, v89, v95
.LBB0_764:
	ds_write_b32 v106, v89 offset:6864
	s_and_b64 vcc, exec, s[36:37]
	s_waitcnt vmcnt(4)
	v_cndmask_b32_e64 v89, 0, v133, s[0:1]
	s_cbranch_vccnz .LBB0_766
	global_load_dword v95, v[92:93], off offset:216 nt
	s_waitcnt vmcnt(0)
	v_mul_f32_e32 v89, v89, v95
.LBB0_766:
	ds_write_b32 v106, v89 offset:7128
	s_and_b64 vcc, exec, s[36:37]
	s_waitcnt vmcnt(3)
	v_cndmask_b32_e64 v89, 0, v134, s[0:1]
	s_cbranch_vccnz .LBB0_768
	global_load_dword v95, v[92:93], off offset:224 nt
	s_waitcnt vmcnt(0)
	v_mul_f32_e32 v89, v89, v95
.LBB0_768:
	ds_write_b32 v106, v89 offset:7392
	s_and_b64 vcc, exec, s[36:37]
	s_waitcnt vmcnt(2)
	v_cndmask_b32_e64 v89, 0, v135, s[0:1]
	s_cbranch_vccnz .LBB0_770
	global_load_dword v95, v[92:93], off offset:232 nt
	s_waitcnt vmcnt(0)
	v_mul_f32_e32 v89, v89, v95
.LBB0_770:
	ds_write_b32 v106, v89 offset:7656
	s_and_b64 vcc, exec, s[36:37]
	s_waitcnt vmcnt(1)
	v_cndmask_b32_e64 v89, 0, v136, s[0:1]
	s_cbranch_vccnz .LBB0_772
	global_load_dword v95, v[92:93], off offset:240 nt
	s_waitcnt vmcnt(0)
	v_mul_f32_e32 v89, v89, v95
.LBB0_772:
	ds_write_b32 v106, v89 offset:7920
	s_and_b64 vcc, exec, s[36:37]
	s_waitcnt vmcnt(0)
	v_cndmask_b32_e64 v89, 0, v94, s[0:1]
	s_cbranch_vccnz .LBB0_774
	global_load_dword v92, v[92:93], off offset:248 nt
	s_waitcnt vmcnt(0)
	v_mul_f32_e32 v89, v89, v92

; __device__ __forceinline__ CvtItem cvt_decode(const Args& A, const int it) {
;     ...
;     const int kb = r / nblk, nb = r % nblk; c.k0 = 64 * kb; c.n0 = 32 * nb; c.spec = (kind == 2) && (c.n0 >= 3072);
;     c.W = W0; c.col0 = c.n0;
;     if (kind == 0) { const int pn = c.n0 >> 8, bj = (c.n0 >> 7) & 1, jj = c.n0 & 127; c.W = bj ? W1 : W0; c.col0 = pn * 128 + jj; }
;     if (kind == 2) c.col0 = (c.n0 < 1024) ? c.n0 : c.n0 + 16;
;     return c;
; }
; __device__ __forceinline__ void cvt_load(const CvtItem& c, const int lane, f32x4 (&vv)[8], float (&gv)[8]) {
;     const int kr = lane >> 3, nq = lane & 7;
;     if (!c.spec) {
; #pragma unroll
;         for (int i = 0; i < 8; ++i) vv[i] = *(const f32x4*)(c.W + (size_t)(c.k0 + 8 * i + kr) * c.Nsrc + c.col0 + 4 * nq);
; #pragma unroll
;         for (int i = 0; i < 8; ++i) gv[i] = c.gain ? c.gain[c.k0 + 8 * i + kr] : 1.0f;
.LBB0_812:
	s_sext_i32_i16 s0, s18
	s_waitcnt vmcnt(6)
	v_cvt_f32_i32_e32 v5, s0
	s_sext_i32_i16 s1, s17
	s_waitcnt vmcnt(0)
	v_cvt_f32_i32_e32 v8, s1
	s_xor_b32 s0, s1, s0
	s_waitcnt lgkmcnt(0)
	v_rcp_iflag_f32_e32 v9, v5
	s_ashr_i32 s0, s0, 30
	s_or_b32 s8, s0, 1
	v_and_b32_e32 v20, 63, v244
	v_mul_f32_e32 v9, v8, v9
	v_trunc_f32_e32 v9, v9
	v_fma_f32 v8, -v9, v5, v8
	v_cvt_i32_f32_e32 v9, v9
	v_cmp_ge_f32_e64 s[0:1], |v8|, |v5|
	s_and_b64 s[0:1], s[0:1], exec
	s_cselect_b32 s0, s8, 0
	v_readfirstlane_b32 s1, v9
	s_add_i32 s0, s1, s0
	s_sext_i32_i16 s15, s0
	s_mul_i32 s0, s0, s18
	s_sub_i32 s8, s17, s0
	s_sext_i32_i16 s14, s8
	s_lshl_b32 s44, s14, 5
	s_cmpk_gt_i32 s14, 0x5f
	s_cselect_b64 s[0:1], -1, 0
	s_bitcmp0_b32 s8, 2
	s_cselect_b64 vcc, -1, 0
	v_cndmask_b32_e32 v5, v6, v2, vcc
	v_cndmask_b32_e32 v6, v7, v3, vcc
	v_cndmask_b32_e64 v86, v2, v5, s[10:11]
	s_and_b64 s[8:9], s[12:13], s[0:1]
	v_lshlrev_b32_e32 v2, 2, v20
	v_cndmask_b32_e64 v87, v3, v6, s[10:11]
	s_lshl_b32 s20, s15, 6
	s_mov_b64 s[0:1], -1
	s_andn2_b64 vcc, exec, s[8:9]
	v_lshrrev_b32_e32 v21, 3, v20
	v_and_b32_e32 v14, 28, v2
	s_cbranch_vccz .LBB0_824
	s_or_b32 s0, s44, 16
	s_cmp_lt_i32 s14, 32
	s_cselect_b32 s15, s44, s0
	s_lshl_b32 s0, s14, 4
	s_and_b32 s0, s0, 0xffffff80
	s_and_b32 s1, s44, 0x60
	s_or_b32 s14, s0, s1
	s_and_b64 s[0:1], s[10:11], exec
	s_cselect_b32 s10, s14, s44
	s_and_b64 s[0:1], s[12:13], exec
	v_lshrrev_b32_e32 v96, 3, v20
	s_cselect_b32 s0, s15, s10
	v_and_b32_e32 v16, 28, v2
	v_or_b32_e32 v2, s20, v96
	v_mul_hi_i32_i24_e32 v7, s42, v2
	v_mul_i32_i24_e32 v6, s42, v2
	s_ashr_i32 s1, s0, 31
	v_or_b32_e32 v3, 8, v2
	v_lshl_add_u64 v[6:7], v[6:7], 2, v[86:87]
	s_lshl_b64 s[0:1], s[0:1], 2
	v_mul_hi_i32_i24_e32 v11, s42, v3
	v_mul_i32_i24_e32 v10, s42, v3
	v_lshl_add_u64 v[6:7], v[6:7], 0, s[0:1]
	v_lshlrev_b32_e32 v8, 2, v16
	v_mov_b32_e32 v9, v4
	v_lshl_add_u64 v[10:11], v[10:11], 2, v[86:87]
	v_lshl_add_u64 v[6:7], v[6:7], 0, v[8:9]
	v_lshl_add_u64 v[10:11], v[10:11], 0, s[0:1]
	v_or_b32_e32 v3, 16, v2
	v_lshl_add_u64 v[10:11], v[10:11], 0, v[8:9]
	global_load_dwordx4 v[22:25], v[6:7], off nt
	global_load_dwordx4 v[26:29], v[10:11], off nt
	v_mul_hi_i32_i24_e32 v7, s42, v3
	v_mul_i32_i24_e32 v6, s42, v3
	v_or_b32_e32 v3, 24, v2
	v_lshl_add_u64 v[6:7], v[6:7], 2, v[86:87]
	v_mul_hi_i32_i24_e32 v11, s42, v3
	v_mul_i32_i24_e32 v10, s42, v3
	v_lshl_add_u64 v[6:7], v[6:7], 0, s[0:1]
	v_lshl_add_u64 v[10:11], v[10:11], 2, v[86:87]
	v_lshl_add_u64 v[6:7], v[6:7], 0, v[8:9]
	v_lshl_add_u64 v[10:11], v[10:11], 0, s[0:1]
	v_or_b32_e32 v3, 32, v2
	v_lshl_add_u64 v[10:11], v[10:11], 0, v[8:9]
	global_load_dwordx4 v[30:33], v[6:7], off nt
	global_load_dwordx4 v[34:37], v[10:11], off nt
	v_mul_hi_i32_i24_e32 v7, s42, v3
	v_mul_i32_i24_e32 v6, s42, v3
	v_or_b32_e32 v3, 40, v2
	v_lshl_add_u64 v[6:7], v[6:7], 2, v[86:87]
	v_mul_hi_i32_i24_e32 v11, s42, v3
	v_mul_i32_i24_e32 v10, s42, v3
	v_lshl_add_u64 v[6:7], v[6:7], 0, s[0:1]
	v_lshl_add_u64 v[10:11], v[10:11], 2, v[86:87]
	v_lshl_add_u64 v[6:7], v[6:7], 0, v[8:9]
	v_lshl_add_u64 v[10:11], v[10:11], 0, s[0:1]
	v_or_b32_e32 v3, 48, v2
	v_lshl_add_u64 v[10:11], v[10:11], 0, v[8:9]
	global_load_dwordx4 v[38:41], v[6:7], off nt
	global_load_dwordx4 v[42:45], v[10:11], off nt
	v_mul_hi_i32_i24_e32 v7, s42, v3
	v_mul_i32_i24_e32 v6, s42, v3
	v_or_b32_e32 v3, 56, v2
	v_lshl_add_u64 v[6:7], v[6:7], 2, v[86:87]
	v_mul_hi_i32_i24_e32 v11, s42, v3
	v_mul_i32_i24_e32 v10, s42, v3
	v_lshl_add_u64 v[6:7], v[6:7], 0, s[0:1]
	v_lshl_add_u64 v[10:11], v[10:11], 2, v[86:87]
	v_lshl_add_u64 v[6:7], v[6:7], 0, v[8:9]
	v_lshl_add_u64 v[10:11], v[10:11], 0, s[0:1]
	v_lshl_add_u64 v[8:9], v[10:11], 0, v[8:9]
	global_load_dwordx4 v[46:49], v[6:7], off nt
	global_load_dwordx4 v[50:53], v[8:9], off nt
	v_ashrrev_i32_e32 v3, 31, v2
	s_cmp_lg_u64 s[6:7], 0
	s_cselect_b64 s[10:11], -1, 0
	s_cmp_eq_u64 s[6:7], 0
	v_lshl_add_u64 v[2:3], v[2:3], 2, s[6:7]
	s_cbranch_scc1 .LBB0_1128
	global_load_dword v6, v[2:3], off nt
	global_load_dword v7, v[2:3], off offset:32 nt
	v_cndmask_b32_e64 v5, 0, 1, s[10:11]
	v_cmp_ne_u32_e64 s[0:1], 1, v5
	s_andn2_b64 vcc, exec, s[10:11]
	s_cbranch_vccnz .LBB0_1129

; __device__ __forceinline__ CvtItem cvt_decode(const Args& A, const int it) {
;     ...
;     const int kb = r / nblk, nb = r % nblk; c.k0 = 64 * kb; c.n0 = 32 * nb; c.spec = (kind == 2) && (c.n0 >= 3072);
;     c.W = W0; c.col0 = c.n0;
;     if (kind == 0) { const int pn = c.n0 >> 8, bj = (c.n0 >> 7) & 1, jj = c.n0 & 127; c.W = bj ? W1 : W0; c.col0 = pn * 128 + jj; }
;     if (kind == 2) c.col0 = (c.n0 < 1024) ? c.n0 : c.n0 + 16;
;     return c;
; }
; __device__ __forceinline__ void cvt_load(const CvtItem& c, const int lane, f32x4 (&vv)[8], float (&gv)[8]) {
;     const int kr = lane >> 3, nq = lane & 7;
;     if (!c.spec) {
; #pragma unroll
;         for (int i = 0; i < 8; ++i) vv[i] = *(const f32x4*)(c.W + (size_t)(c.k0 + 8 * i + kr) * c.Nsrc + c.col0 + 4 * nq);
; #pragma unroll
;         for (int i = 0; i < 8; ++i) gv[i] = c.gain ? c.gain[c.k0 + 8 * i + kr] : 1.0f;
; __device__ __forceinline__ void convert_weights(const Args& A, LAS unsigned char* ldsl, int wave, int lane, const CvtList Lst, int gw, int NGW) {
;     ...
;         CvtItem nxt = cur; f32x4 vb[8]; float gb[8];
; #pragma unroll
;         for (int i = 0; i < 8; ++i) { vb[i] = va[i]; gb[i] = ga[i]; }
;         if (more) { nxt = cvt_decode(A, CVT_MAP(vn)); cvt_load(nxt, lane, vb, gb); }
.LBB0_848:
	s_sext_i32_i16 s0, s37
	v_cvt_f32_i32_e32 v18, s0
	s_sext_i32_i16 s1, s36
	v_cvt_f32_i32_e32 v19, s1
	s_xor_b32 s0, s1, s0
	v_rcp_iflag_f32_e32 v20, v18
	s_ashr_i32 s0, s0, 30
	s_or_b32 s12, s0, 1
	v_mov_b64_e32 v[56:57], v[24:25]
	v_mul_f32_e32 v20, v19, v20
	v_trunc_f32_e32 v20, v20
	v_fma_f32 v19, -v20, v18, v19
	v_cvt_i32_f32_e32 v20, v20
	v_cmp_ge_f32_e64 s[0:1], |v19|, |v18|
	s_and_b64 s[0:1], s[0:1], exec
	s_cselect_b32 s0, s12, 0
	v_readfirstlane_b32 s1, v20
	s_add_i32 s0, s1, s0
	s_sext_i32_i16 s1, s0
	s_mul_i32 s0, s0, s37
	s_sub_i32 s19, s36, s0
	s_sext_i32_i16 s0, s19
	s_lshl_b32 s18, s0, 5
	s_cmpk_gt_i32 s0, 0x5f
	s_cselect_b64 s[12:13], -1, 0
	s_bitcmp0_b32 s19, 2
	s_cselect_b64 vcc, -1, 0
	v_cndmask_b32_e32 v16, v16, v14, vcc
	v_cndmask_b32_e32 v17, v17, v15, vcc
	v_cndmask_b32_e64 v91, v15, v17, s[14:15]
	v_cndmask_b32_e64 v90, v14, v16, s[14:15]
	s_and_b64 s[12:13], s[16:17], s[12:13]
	v_mov_b64_e32 v[20:21], v[12:13]
	v_mov_b64_e32 v[60:61], v[28:29]
	v_mov_b64_e32 v[64:65], v[32:33]
	v_mov_b64_e32 v[68:69], v[36:37]
	v_mov_b64_e32 v[72:73], v[40:41]
	v_mov_b64_e32 v[76:77], v[44:45]
	v_mov_b64_e32 v[80:81], v[48:49]
	v_mov_b64_e32 v[84:85], v[52:53]
	s_lshl_b32 s19, s1, 6
	s_mov_b64 s[40:41], -1
	s_and_b64 vcc, exec, s[12:13]
	v_mov_b64_e32 v[18:19], v[10:11]
	v_mov_b64_e32 v[16:17], v[8:9]
	v_mov_b64_e32 v[14:15], v[6:7]
	v_mov_b64_e32 v[54:55], v[22:23]
	v_mov_b64_e32 v[58:59], v[26:27]
	v_mov_b64_e32 v[62:63], v[30:31]
	v_mov_b64_e32 v[66:67], v[34:35]
	v_mov_b64_e32 v[70:71], v[38:39]
	v_mov_b64_e32 v[74:75], v[42:43]
	v_mov_b64_e32 v[78:79], v[46:47]
	v_mov_b64_e32 v[82:83], v[50:51]
	s_cbranch_vccnz .LBB0_862
	s_or_b32 s1, s18, 16
	s_cmp_lt_i32 s0, 32
	s_cselect_b32 s12, s18, s1
	s_lshl_b32 s0, s0, 4
	s_and_b32 s0, s0, 0xffffff80
	s_and_b32 s1, s18, 0x60
	s_or_b32 s13, s0, s1
	s_and_b64 s[0:1], s[14:15], exec
	s_cselect_b32 s13, s13, s18
	s_and_b64 s[0:1], s[16:17], exec
	s_cselect_b32 s0, s12, s13
	v_or_b32_e32 v14, s19, v96
	v_mul_hi_i32_i24_e32 v17, s45, v14
	v_mul_i32_i24_e32 v16, s45, v14
	s_ashr_i32 s1, s0, 31
	v_or_b32_e32 v15, 8, v14
	v_lshl_add_u64 v[16:17], v[16:17], 2, v[90:91]
	s_lshl_b64 s[0:1], s[0:1], 2
	v_mul_hi_i32_i24_e32 v19, s45, v15
	v_mul_i32_i24_e32 v18, s45, v15
	v_lshl_add_u64 v[16:17], v[16:17], 0, s[0:1]
	v_lshl_add_u64 v[18:19], v[18:19], 2, v[90:91]
	v_lshl_add_u64 v[16:17], v[16:17], 0, v[2:3]
	v_lshl_add_u64 v[18:19], v[18:19], 0, s[0:1]
	v_or_b32_e32 v15, 16, v14
	v_lshl_add_u64 v[18:19], v[18:19], 0, v[2:3]
	global_load_dwordx4 v[54:57], v[16:17], off nt
	global_load_dwordx4 v[58:61], v[18:19], off nt
	v_mul_hi_i32_i24_e32 v17, s45, v15
	v_mul_i32_i24_e32 v16, s45, v15
	v_or_b32_e32 v15, 24, v14
	v_lshl_add_u64 v[16:17], v[16:17], 2, v[90:91]
	v_mul_hi_i32_i24_e32 v19, s45, v15
	v_mul_i32_i24_e32 v18, s45, v15
	v_lshl_add_u64 v[16:17], v[16:17], 0, s[0:1]
	v_lshl_add_u64 v[18:19], v[18:19], 2, v[90:91]
	v_lshl_add_u64 v[16:17], v[16:17], 0, v[2:3]
	v_lshl_add_u64 v[18:19], v[18:19], 0, s[0:1]
	v_or_b32_e32 v15, 32, v14
	v_lshl_add_u64 v[18:19], v[18:19], 0, v[2:3]
	global_load_dwordx4 v[62:65], v[16:17], off nt
	global_load_dwordx4 v[66:69], v[18:19], off nt
	v_mul_hi_i32_i24_e32 v17, s45, v15
	v_mul_i32_i24_e32 v16, s45, v15
	v_or_b32_e32 v15, 40, v14
	v_lshl_add_u64 v[16:17], v[16:17], 2, v[90:91]
	v_mul_hi_i32_i24_e32 v19, s45, v15
	v_mul_i32_i24_e32 v18, s45, v15
	v_lshl_add_u64 v[16:17], v[16:17], 0, s[0:1]
	v_lshl_add_u64 v[18:19], v[18:19], 2, v[90:91]
	v_lshl_add_u64 v[16:17], v[16:17], 0, v[2:3]
	v_lshl_add_u64 v[18:19], v[18:19], 0, s[0:1]
	v_or_b32_e32 v15, 48, v14
	v_lshl_add_u64 v[18:19], v[18:19], 0, v[2:3]
	global_load_dwordx4 v[70:73], v[16:17], off nt
	global_load_dwordx4 v[74:77], v[18:19], off nt
	v_mul_hi_i32_i24_e32 v17, s45, v15
	v_mul_i32_i24_e32 v16, s45, v15
	v_or_b32_e32 v15, 56, v14
	v_lshl_add_u64 v[16:17], v[16:17], 2, v[90:91]
	v_mul_hi_i32_i24_e32 v19, s45, v15
	v_mul_i32_i24_e32 v18, s45, v15
	v_lshl_add_u64 v[16:17], v[16:17], 0, s[0:1]
	v_lshl_add_u64 v[18:19], v[18:19], 2, v[90:91]
	v_lshl_add_u64 v[16:17], v[16:17], 0, v[2:3]
	v_lshl_add_u64 v[18:19], v[18:19], 0, s[0:1]
	v_lshl_add_u64 v[18:19], v[18:19], 0, v[2:3]
	global_load_dwordx4 v[78:81], v[16:17], off nt
	global_load_dwordx4 v[82:85], v[18:19], off nt
	v_ashrrev_i32_e32 v15, 31, v14
	s_cmp_lg_u64 s[38:39], 0
	s_cselect_b64 s[12:13], -1, 0
	s_cmp_eq_u64 s[38:39], 0
	v_lshl_add_u64 v[92:93], v[14:15], 2, s[38:39]
	s_cbranch_scc1 .LBB0_932
	global_load_dword v14, v[92:93], off nt
	global_load_dword v15, v[92:93], off offset:32 nt
	s_cbranch_execnz .LBB0_852

; __device__ __forceinline__ void cvt_finish(const CvtItem& c, const int lane, LAS float* scr, const f32x4 (&vv)[8], const float (&gv)[8]) {
;     ...
;         const int np = c.n0 + (lane & 31);
;         int col = 0; bool valid = true;
;         if (np < 3088) col = 1024 + (np - 3072); else if (np < NIN) col = np; else valid = false;
;         float ev[32];
; #pragma unroll
;         for (int i = 0; i < 32; ++i) ev[i] = c.W[(size_t)(c.k0 + 2 * i + (lane >> 5)) * c.Nsrc + col];
.LBB0_864:
	s_andn2_b64 vcc, exec, s[0:1]
	s_cbranch_vccnz .LBB0_930
	v_add_u32_e32 v89, s44, v99
	s_movk_i32 s0, 0xc10
	s_movk_i32 s12, 0xc14
	v_cmp_gt_i32_e32 vcc, s0, v89
	v_cmp_gt_u32_e64 s[0:1], s12, v89
	v_add_u32_e32 v92, 0xfffff800, v89
	s_cmp_lg_u64 s[6:7], 0
	v_cndmask_b32_e64 v93, 0, v89, s[0:1]
	v_cndmask_b32_e32 v94, v93, v92, vcc
	v_add_u32_e32 v92, s20, v100
	v_mad_u64_u32 v[108:109], s[0:1], v92, s42, 0
	v_ashrrev_i32_e32 v93, 31, v92
	v_mov_b32_e32 v110, v109
	v_ashrrev_i32_e32 v95, 31, v94
	v_mad_u64_u32 v[110:111], s[0:1], v93, s42, v[110:111]
	v_lshl_add_u64 v[94:95], v[94:95], 2, v[86:87]
	v_mov_b32_e32 v109, v110
	v_lshl_add_u64 v[108:109], v[108:109], 2, v[94:95]
	global_load_dword v113, v[108:109], off nt
	v_add_u32_e32 v107, 2, v92
	v_mad_u64_u32 v[108:109], s[0:1], v107, s42, 0
	v_ashrrev_i32_e32 v111, 31, v107
	v_mov_b32_e32 v110, v109
	v_mad_u64_u32 v[110:111], s[0:1], v111, s42, v[110:111]
	v_mov_b32_e32 v109, v110
	v_lshl_add_u64 v[108:109], v[108:109], 2, v[94:95]
	global_load_dword v107, v[108:109], off nt
	v_add_u32_e32 v108, 4, v92
	v_ashrrev_i32_e32 v111, 31, v108
	v_mad_u64_u32 v[108:109], s[0:1], v108, s42, 0
	v_mov_b32_e32 v110, v109
	v_mad_u64_u32 v[110:111], s[0:1], v111, s42, v[110:111]
	v_mov_b32_e32 v109, v110
	v_lshl_add_u64 v[108:109], v[108:109], 2, v[94:95]
	global_load_dword v108, v[108:109], off nt
	v_add_u32_e32 v109, 6, v92
	v_mad_u64_u32 v[110:111], s[0:1], v109, s42, 0
	v_ashrrev_i32_e32 v114, 31, v109
	v_mov_b32_e32 v112, v111
	s_waitcnt vmcnt(2)
	v_mad_u64_u32 v[114:115], s[0:1], v114, s42, v[112:113]
	v_mov_b32_e32 v111, v114
	v_lshl_add_u64 v[110:111], v[110:111], 2, v[94:95]
	global_load_dword v109, v[110:111], off nt
	v_add_u32_e32 v110, 8, v92
	v_ashrrev_i32_e32 v114, 31, v110
	v_mad_u64_u32 v[110:111], s[0:1], v110, s42, 0
	v_mov_b32_e32 v112, v111
	v_mad_u64_u32 v[114:115], s[0:1], v114, s42, v[112:113]
	v_mov_b32_e32 v111, v114
	v_lshl_add_u64 v[110:111], v[110:111], 2, v[94:95]
	global_load_dword v110, v[110:111], off nt
	v_add_u32_e32 v111, 10, v92
	v_mad_u64_u32 v[114:115], s[0:1], v111, s42, 0
	v_ashrrev_i32_e32 v116, 31, v111
	v_mov_b32_e32 v112, v115
	v_mad_u64_u32 v[116:117], s[0:1], v116, s42, v[112:113]
	v_mov_b32_e32 v115, v116
	v_lshl_add_u64 v[114:115], v[114:115], 2, v[94:95]
	v_add_u32_e32 v112, 12, v92
	global_load_dword v111, v[114:115], off nt
	v_mad_u64_u32 v[114:115], s[0:1], v112, s42, 0
	v_ashrrev_i32_e32 v116, 31, v112
	v_mov_b32_e32 v112, v115
	v_mad_u64_u32 v[116:117], s[0:1], v116, s42, v[112:113]
	v_mov_b32_e32 v115, v116
	v_lshl_add_u64 v[114:115], v[114:115], 2, v[94:95]
	global_load_dword v112, v[114:115], off nt
	v_add_u32_e32 v114, 14, v92
	v_ashrrev_i32_e32 v117, 31, v114
	v_mad_u64_u32 v[114:115], s[0:1], v114, s42, 0
	v_mov_b32_e32 v116, v115
	v_mad_u64_u32 v[116:117], s[0:1], v117, s42, v[116:117]
	v_mov_b32_e32 v115, v116
	v_lshl_add_u64 v[114:115], v[114:115], 2, v[94:95]
	global_load_dword v121, v[114:115], off nt
	v_add_u32_e32 v114, 16, v92
	v_ashrrev_i32_e32 v117, 31, v114
	v_mad_u64_u32 v[114:115], s[0:1], v114, s42, 0
	v_mov_b32_e32 v116, v115
	v_mad_u64_u32 v[116:117], s[0:1], v117, s42, v[116:117]
	v_mov_b32_e32 v115, v116
	v_lshl_add_u64 v[114:115], v[114:115], 2, v[94:95]
	global_load_dword v114, v[114:115], off nt
	v_add_u32_e32 v115, 18, v92
	v_mad_u64_u32 v[116:117], s[0:1], v115, s42, 0
	v_ashrrev_i32_e32 v119, 31, v115
	v_mov_b32_e32 v118, v117
	v_mad_u64_u32 v[118:119], s[0:1], v119, s42, v[118:119]
	v_mov_b32_e32 v117, v118
	v_lshl_add_u64 v[116:117], v[116:117], 2, v[94:95]
	global_load_dword v115, v[116:117], off nt
	v_add_u32_e32 v116, 20, v92
	v_ashrrev_i32_e32 v119, 31, v116
	v_mad_u64_u32 v[116:117], s[0:1], v116, s42, 0
	v_mov_b32_e32 v118, v117
	v_mad_u64_u32 v[118:119], s[0:1], v119, s42, v[118:119]
	v_mov_b32_e32 v117, v118
	v_lshl_add_u64 v[116:117], v[116:117], 2, v[94:95]
	global_load_dword v116, v[116:117], off nt
	v_add_u32_e32 v117, 22, v92
	v_mad_u64_u32 v[118:119], s[0:1], v117, s42, 0
	v_ashrrev_i32_e32 v122, 31, v117
	v_mov_b32_e32 v120, v119
	s_waitcnt vmcnt(3)
	v_mad_u64_u32 v[122:123], s[0:1], v122, s42, v[120:121]
	v_mov_b32_e32 v119, v122
	v_lshl_add_u64 v[118:119], v[118:119], 2, v[94:95]
	global_load_dword v117, v[118:119], off nt
	v_add_u32_e32 v118, 24, v92
	v_ashrrev_i32_e32 v122, 31, v118
	v_mad_u64_u32 v[118:119], s[0:1], v118, s42, 0
	v_mov_b32_e32 v120, v119
	v_mad_u64_u32 v[122:123], s[0:1], v122, s42, v[120:121]
	v_mov_b32_e32 v119, v122
	v_lshl_add_u64 v[118:119], v[118:119], 2, v[94:95]
	global_load_dword v118, v[118:119], off nt
	v_add_u32_e32 v119, 26, v92
	v_mad_u64_u32 v[122:123], s[0:1], v119, s42, 0
	v_ashrrev_i32_e32 v124, 31, v119
	v_mov_b32_e32 v120, v123
	v_mad_u64_u32 v[124:125], s[0:1], v124, s42, v[120:121]
	v_mov_b32_e32 v123, v124
	v_lshl_add_u64 v[122:123], v[122:123], 2, v[94:95]
	v_add_u32_e32 v120, 28, v92
	global_load_dword v119, v[122:123], off nt
	v_mad_u64_u32 v[122:123], s[0:1], v120, s42, 0
	v_ashrrev_i32_e32 v124, 31, v120
	v_mov_b32_e32 v120, v123
	v_mad_u64_u32 v[124:125], s[0:1], v124, s42, v[120:121]
	v_mov_b32_e32 v123, v124
	v_lshl_add_u64 v[122:123], v[122:123], 2, v[94:95]
	global_load_dword v120, v[122:123], off nt
	v_add_u32_e32 v122, 30, v92
	v_ashrrev_i32_e32 v125, 31, v122
	v_mad_u64_u32 v[122:123], s[0:1], v122, s42, 0
	v_mov_b32_e32 v124, v123
	v_mad_u64_u32 v[124:125], s[0:1], v125, s42, v[124:125]
	v_mov_b32_e32 v123, v124
	v_lshl_add_u64 v[122:123], v[122:123], 2, v[94:95]
	global_load_dword v129, v[122:123], off nt
	v_add_u32_e32 v122, 32, v92
	v_ashrrev_i32_e32 v125, 31, v122
	v_mad_u64_u32 v[122:123], s[0:1], v122, s42, 0
	v_mov_b32_e32 v124, v123
	v_mad_u64_u32 v[124:125], s[0:1], v125, s42, v[124:125]
	v_mov_b32_e32 v123, v124
	v_lshl_add_u64 v[122:123], v[122:123], 2, v[94:95]
	global_load_dword v122, v[122:123], off nt
	v_add_u32_e32 v123, 34, v92
	v_mad_u64_u32 v[124:125], s[0:1], v123, s42, 0
	v_ashrrev_i32_e32 v127, 31, v123
	v_mov_b32_e32 v126, v125
	v_mad_u64_u32 v[126:127], s[0:1], v127, s42, v[126:127]
	v_mov_b32_e32 v125, v126
	v_lshl_add_u64 v[124:125], v[124:125], 2, v[94:95]
	global_load_dword v123, v[124:125], off nt
	v_add_u32_e32 v124, 36, v92
	v_ashrrev_i32_e32 v127, 31, v124
	v_mad_u64_u32 v[124:125], s[0:1], v124, s42, 0
	v_mov_b32_e32 v126, v125
	v_mad_u64_u32 v[126:127], s[0:1], v127, s42, v[126:127]
	v_mov_b32_e32 v125, v126
	v_lshl_add_u64 v[124:125], v[124:125], 2, v[94:95]
	global_load_dword v124, v[124:125], off nt
	v_add_u32_e32 v125, 38, v92
	v_mad_u64_u32 v[126:127], s[0:1], v125, s42, 0
	v_ashrrev_i32_e32 v130, 31, v125
	v_mov_b32_e32 v128, v127
	s_waitcnt vmcnt(3)
; __device__ __forceinline__ void cvt_finish(const CvtItem& c, const int lane, LAS float* scr, const f32x4 (&vv)[8], const float (&gv)[8]) {
;     ...
;         for (int i = 0; i < 32; ++i) ev[i] = c.W[(size_t)(c.k0 + 2 * i + (lane >> 5)) * c.Nsrc + col];
; #pragma unroll
;         for (int i = 0; i < 32; ++i) { const int kk = 2 * i + (lane >> 5); float v = valid ? ev[i] : 0.f; if (c.gain) v *= c.gain[c.k0 + kk]; scr[kk * 33 + (lane & 31)] = v; }
	v_mad_u64_u32 v[130:131], s[0:1], v130, s42, v[128:129]
	v_mov_b32_e32 v127, v130
	v_lshl_add_u64 v[126:127], v[126:127], 2, v[94:95]
	global_load_dword v125, v[126:127], off nt
	v_add_u32_e32 v126, 40, v92
	v_ashrrev_i32_e32 v130, 31, v126
	v_mad_u64_u32 v[126:127], s[0:1], v126, s42, 0
	v_mov_b32_e32 v128, v127
	v_mad_u64_u32 v[130:131], s[0:1], v130, s42, v[128:129]
	v_mov_b32_e32 v127, v130
	v_lshl_add_u64 v[126:127], v[126:127], 2, v[94:95]
	global_load_dword v126, v[126:127], off nt
	v_add_u32_e32 v127, 42, v92
	v_mad_u64_u32 v[130:131], s[0:1], v127, s42, 0
	v_ashrrev_i32_e32 v132, 31, v127
	v_mov_b32_e32 v128, v131
	v_mad_u64_u32 v[132:133], s[0:1], v132, s42, v[128:129]
	v_mov_b32_e32 v131, v132
	v_lshl_add_u64 v[130:131], v[130:131], 2, v[94:95]
	v_add_u32_e32 v128, 44, v92
	global_load_dword v127, v[130:131], off nt
	v_mad_u64_u32 v[130:131], s[0:1], v128, s42, 0
	v_ashrrev_i32_e32 v132, 31, v128
	v_mov_b32_e32 v128, v131
	v_mad_u64_u32 v[132:133], s[0:1], v132, s42, v[128:129]
	v_mov_b32_e32 v131, v132
	v_lshl_add_u64 v[130:131], v[130:131], 2, v[94:95]
	global_load_dword v128, v[130:131], off nt
	v_add_u32_e32 v130, 46, v92
	v_ashrrev_i32_e32 v133, 31, v130
	v_mad_u64_u32 v[130:131], s[0:1], v130, s42, 0
	v_mov_b32_e32 v132, v131
	v_mad_u64_u32 v[132:133], s[0:1], v133, s42, v[132:133]
	v_mov_b32_e32 v131, v132
	v_lshl_add_u64 v[130:131], v[130:131], 2, v[94:95]
	global_load_dword v137, v[130:131], off nt
	v_add_u32_e32 v130, 48, v92
	v_ashrrev_i32_e32 v133, 31, v130
	v_mad_u64_u32 v[130:131], s[0:1], v130, s42, 0
	v_mov_b32_e32 v132, v131
	v_mad_u64_u32 v[132:133], s[0:1], v133, s42, v[132:133]
	v_mov_b32_e32 v131, v132
	v_lshl_add_u64 v[130:131], v[130:131], 2, v[94:95]
	global_load_dword v130, v[130:131], off nt
	v_add_u32_e32 v131, 50, v92
	v_mad_u64_u32 v[132:133], s[0:1], v131, s42, 0
	v_ashrrev_i32_e32 v135, 31, v131
	v_mov_b32_e32 v134, v133
	v_mad_u64_u32 v[134:135], s[0:1], v135, s42, v[134:135]
	v_mov_b32_e32 v133, v134
	v_lshl_add_u64 v[132:133], v[132:133], 2, v[94:95]
	global_load_dword v131, v[132:133], off nt
	v_add_u32_e32 v132, 52, v92
	v_ashrrev_i32_e32 v135, 31, v132
	v_mad_u64_u32 v[132:133], s[0:1], v132, s42, 0
	v_mov_b32_e32 v134, v133
	v_mad_u64_u32 v[134:135], s[0:1], v135, s42, v[134:135]
	v_mov_b32_e32 v133, v134
	v_lshl_add_u64 v[132:133], v[132:133], 2, v[94:95]
	global_load_dword v132, v[132:133], off nt
	v_add_u32_e32 v133, 54, v92
	v_mad_u64_u32 v[134:135], s[0:1], v133, s42, 0
	v_ashrrev_i32_e32 v138, 31, v133
	v_mov_b32_e32 v136, v135
	s_waitcnt vmcnt(3)
	v_mad_u64_u32 v[138:139], s[0:1], v138, s42, v[136:137]
	v_mov_b32_e32 v135, v138
	v_lshl_add_u64 v[134:135], v[134:135], 2, v[94:95]
	global_load_dword v133, v[134:135], off nt
	v_add_u32_e32 v134, 56, v92
	v_ashrrev_i32_e32 v138, 31, v134
	v_mad_u64_u32 v[134:135], s[0:1], v134, s42, 0
	v_mov_b32_e32 v136, v135
	v_mad_u64_u32 v[138:139], s[0:1], v138, s42, v[136:137]
	v_mov_b32_e32 v135, v138
	v_lshl_add_u64 v[134:135], v[134:135], 2, v[94:95]
	global_load_dword v134, v[134:135], off nt
	v_add_u32_e32 v135, 58, v92
	v_mad_u64_u32 v[138:139], s[0:1], v135, s42, 0
	v_ashrrev_i32_e32 v140, 31, v135
	v_mov_b32_e32 v136, v139
	v_mad_u64_u32 v[140:141], s[0:1], v140, s42, v[136:137]
	v_mov_b32_e32 v139, v140
	v_lshl_add_u64 v[138:139], v[138:139], 2, v[94:95]
	v_add_u32_e32 v136, 60, v92
	global_load_dword v135, v[138:139], off nt
	v_mad_u64_u32 v[138:139], s[0:1], v136, s42, 0
	v_ashrrev_i32_e32 v140, 31, v136
	v_mov_b32_e32 v136, v139
	v_mad_u64_u32 v[140:141], s[0:1], v140, s42, v[136:137]
	v_mov_b32_e32 v139, v140
	v_lshl_add_u64 v[138:139], v[138:139], 2, v[94:95]
	global_load_dword v136, v[138:139], off nt
	v_add_u32_e32 v138, 62, v92
	v_ashrrev_i32_e32 v141, 31, v138
	v_mad_u64_u32 v[138:139], s[0:1], v138, s42, 0
	v_mov_b32_e32 v140, v139
	v_mad_u64_u32 v[140:141], s[0:1], v141, s42, v[140:141]
	v_mov_b32_e32 v139, v140
	v_lshl_add_u64 v[94:95], v[138:139], 2, v[94:95]
	global_load_dword v94, v[94:95], off nt
	v_cmp_gt_i32_e64 s[0:1], s12, v89
	s_cselect_b64 s[12:13], -1, 0
	s_cmp_eq_u64 s[6:7], 0
	v_cndmask_b32_e64 v89, 0, v113, s[0:1]
	v_lshl_add_u64 v[92:93], v[92:93], 2, s[6:7]
	s_cbranch_scc1 .LBB0_867
	global_load_dword v95, v[92:93], off nt
	s_waitcnt vmcnt(0)
	v_mul_f32_e32 v89, v89, v95

; __device__ __forceinline__ void final_phase(const Args& A, int wave, int lane, int G) {
;     const int gw = blockIdx.x * NWAVES + wave, NGW = G * NWAVES;
;     const float* rss = (const float*)(A.ws + WS_RSS) + (size_t)6 * M; const f32x4* gn = (const f32x4*)A.in[I_FINALN] + lane; const bf16* xb = (const bf16*)(A.ws + WS_XB);
;     f32x4 g4[4];
; #pragma unroll
;     for (int j = 0; j < 4; ++j) g4[j] = gn[64 * j];
;     for (int m0 = gw; m0 < M; m0 += 2 * NGW) {
;         const int m1 = m0 + NGW; const bool two = m1 < M; const int m1c = two ? m1 : m0;
;         const float q0 = rss[m0], q1 = rss[m1c];
;         const v2u* x0 = (const v2u*)(xb + (size_t)m0 * D) + lane; const v2u* x1 = (const v2u*)(xb + (size_t)m1c * D) + lane;
;         v2u w0[4], w1[4];
; #pragma unroll
;         for (int j = 0; j < 4; ++j) { w0[j] = x0[64 * j]; w1[j] = x1[64 * j]; }
.LBB0_939:
	s_and_b64 vcc, exec, s[0:1]
	s_cbranch_vccz .LBB0_945
	v_readfirstlane_b32 s0, v244
	s_ashr_i32 s0, s0, 6
	v_readlane_b32 s1, v252, 47
	s_add_i32 s4, s0, s1
	s_cmpk_gt_i32 s4, 0x43ff
	s_cbranch_scc1 .LBB0_945
	v_and_b32_e32 v2, 63, v244
	v_readlane_b32 s36, v254, 3
	s_waitcnt vmcnt(4)
	v_lshlrev_b32_e32 v22, 4, v2
	v_readlane_b32 s50, v254, 17
	v_readlane_b32 s51, v254, 18
	s_waitcnt lgkmcnt(0)
	s_nop 3
	global_load_dwordx4 v[6:9], v22, s[50:51] nt
	global_load_dwordx4 v[10:13], v22, s[50:51] offset:1024 nt
	global_load_dwordx4 v[14:17], v22, s[50:51] offset:2048 nt
	global_load_dwordx4 v[18:21], v22, s[50:51] offset:3072 nt
	v_mov_b32_e32 v23, v4
	v_lshlrev_b32_e32 v2, 3, v2
	v_mov_b32_e32 v3, v4
	v_lshl_add_u64 v[2:3], s[84:85], 0, v[2:3]
	v_lshl_add_u64 v[22:23], s[60:61], 0, v[22:23]
	v_readlane_b32 s37, v254, 4
	v_readlane_b32 s38, v254, 5
	v_readlane_b32 s39, v254, 6
	v_readlane_b32 s40, v254, 7
	v_readlane_b32 s41, v254, 8
	v_readlane_b32 s42, v254, 9
	v_readlane_b32 s43, v254, 10
	v_readlane_b32 s44, v254, 11
	v_readlane_b32 s45, v254, 12
	v_readlane_b32 s46, v254, 13
	v_readlane_b32 s47, v254, 14
	v_readlane_b32 s48, v254, 15
	v_readlane_b32 s49, v254, 16
	s_branch .LBB0_943

; __device__ __forceinline__ void final_phase(const Args& A, int wave, int lane, int G) {
;     ...
;     for (int m0 = gw; m0 < M; m0 += 2 * NGW) {
;         const int m1 = m0 + NGW; const bool two = m1 < M; const int m1c = two ? m1 : m0;
;         const float q0 = rss[m0], q1 = rss[m1c];
;         const v2u* x0 = (const v2u*)(xb + (size_t)m0 * D) + lane; const v2u* x1 = (const v2u*)(xb + (size_t)m1c * D) + lane;
;         v2u w0[4], w1[4];
; #pragma unroll
;         for (int j = 0; j < 4; ++j) { w0[j] = x0[64 * j]; w1[j] = x1[64 * j]; }
;         const float r0 = rsqrtf(q0 * (1.0f / 1024.0f) + 1e-6f), r1 = rsqrtf(q1 * (1.0f / 1024.0f) + 1e-6f);
;         f32x4* y0 = (f32x4*)(A.out + (size_t)m0 * D) + lane; f32x4* y1 = (f32x4*)(A.out + (size_t)m1c * D) + lane;
; #pragma unroll
;         for (int j = 0; j < 4; ++j) { const v2u w = w0[j]; const f32x4 v = {__builtin_bit_cast(float, w.x << 16), __builtin_bit_cast(float, w.x & 0xffff0000u), __builtin_bit_cast(float, w.y << 16), __builtin_bit_cast(float, w.y & 0xffff0000u)};
;             y0[64 * j] = v * r0 * g4[j]; }
;         if (two) {
; #pragma unroll
;             for (int j = 0; j < 4; ++j) { const v2u w = w1[j]; const f32x4 v = {__builtin_bit_cast(float, w.x << 16), __builtin_bit_cast(float, w.x & 0xffff0000u), __builtin_bit_cast(float, w.y << 16), __builtin_bit_cast(float, w.y & 0xffff0000u)};
;                 y1[64 * j] = v * r1 * g4[j]; }
;         }
.LBB0_943:
	s_add_i32 s3, s4, s96
	s_cmpk_lt_i32 s3, 0x4400
	s_cselect_b32 s0, s3, s4
	s_ashr_i32 s5, s4, 31
	s_lshl_b64 s[6:7], s[4:5], 2
	v_readlane_b32 s10, v252, 48
	s_add_u32 s6, s10, s6
	v_readlane_b32 s11, v252, 49
	s_addc_u32 s7, s11, s7
	global_load_dword v40, v4, s[6:7] nt
	s_ashr_i32 s1, s0, 31
	s_lshl_b64 s[8:9], s[0:1], 2
	s_add_u32 s6, s10, s8
	s_addc_u32 s7, s11, s9
	s_lshl_b64 s[8:9], s[4:5], 11
	s_waitcnt vmcnt(5)
	v_lshl_add_u64 v[24:25], v[2:3], 0, s[8:9]
	s_lshl_b64 s[8:9], s[0:1], 11
	global_load_dwordx2 v[32:33], v[24:25], off nt
	global_load_dwordx2 v[34:35], v[24:25], off offset:512 nt
	global_load_dwordx2 v[36:37], v[24:25], off offset:1024 nt
	global_load_dwordx2 v[38:39], v[24:25], off offset:1536 nt
	v_lshl_add_u64 v[24:25], v[2:3], 0, s[8:9]
	global_load_dwordx2 v[28:29], v[24:25], off offset:512 nt
	global_load_dwordx2 v[30:31], v[24:25], off nt
	global_load_dword v5, v4, s[6:7] nt
	global_load_dwordx2 v[26:27], v[24:25], off offset:1024 nt
	s_nop 0
	global_load_dwordx2 v[24:25], v[24:25], off offset:1536 nt
	s_lshl_b64 s[4:5], s[4:5], 12
	v_lshl_add_u64 v[48:49], v[22:23], 0, s[4:5]
	s_mov_b32 s4, 0x800000
	s_cmpk_gt_i32 s3, 0x43ff
	s_waitcnt vmcnt(9)
	v_fmamk_f32 v40, v40, 0x3a800000, v231
	v_mul_f32_e32 v41, 0x4b800000, v40
	v_cmp_gt_f32_e32 vcc, s4, v40
	s_waitcnt vmcnt(7)
	v_lshlrev_b32_e32 v42, 16, v34
	v_cndmask_b32_e32 v40, v40, v41, vcc
	v_rsq_f32_e32 v50, v40
	v_lshlrev_b32_e32 v40, 16, v32
	v_and_b32_e32 v41, 0xffff0000, v32
	v_lshlrev_b32_e32 v32, 16, v33
	v_mul_f32_e32 v51, 0x45800000, v50
	v_and_b32_e32 v33, 0xffff0000, v33
	v_cndmask_b32_e32 v50, v50, v51, vcc
	v_and_b32_e32 v43, 0xffff0000, v34
	v_lshlrev_b32_e32 v34, 16, v35
	v_and_b32_e32 v35, 0xffff0000, v35
	s_waitcnt vmcnt(6)
	v_lshlrev_b32_e32 v44, 16, v36
	v_and_b32_e32 v45, 0xffff0000, v36
	v_lshlrev_b32_e32 v36, 16, v37
	v_and_b32_e32 v37, 0xffff0000, v37
	s_waitcnt vmcnt(5)
	v_lshlrev_b32_e32 v46, 16, v38
	v_and_b32_e32 v47, 0xffff0000, v38
	v_lshlrev_b32_e32 v38, 16, v39
	v_and_b32_e32 v39, 0xffff0000, v39
	v_pk_mul_f32 v[40:41], v[50:51], v[40:41] op_sel_hi:[0,1]
	v_pk_mul_f32 v[32:33], v[50:51], v[32:33] op_sel_hi:[0,1]
	v_pk_mul_f32 v[42:43], v[50:51], v[42:43] op_sel_hi:[0,1]
	v_pk_mul_f32 v[52:53], v[50:51], v[34:35] op_sel_hi:[0,1]
	v_pk_mul_f32 v[44:45], v[50:51], v[44:45] op_sel_hi:[0,1]
	v_pk_mul_f32 v[54:55], v[50:51], v[36:37] op_sel_hi:[0,1]
	v_pk_mul_f32 v[56:57], v[50:51], v[46:47] op_sel_hi:[0,1]
	v_pk_mul_f32 v[46:47], v[50:51], v[38:39] op_sel_hi:[0,1]
	v_pk_mul_f32 v[34:35], v[8:9], v[32:33]
	v_pk_mul_f32 v[32:33], v[6:7], v[40:41]
	v_pk_mul_f32 v[38:39], v[12:13], v[52:53]
	v_pk_mul_f32 v[36:37], v[10:11], v[42:43]
	v_pk_mul_f32 v[42:43], v[16:17], v[54:55]
	v_pk_mul_f32 v[40:41], v[14:15], v[44:45]
	v_pk_mul_f32 v[46:47], v[20:21], v[46:47]
	v_pk_mul_f32 v[44:45], v[18:19], v[56:57]
	global_store_dwordx4 v[48:49], v[32:35], off
	global_store_dwordx4 v[48:49], v[36:39], off offset:1024
	global_store_dwordx4 v[48:49], v[40:43], off offset:2048
	global_store_dwordx4 v[48:49], v[44:47], off offset:3072
	s_cbranch_scc1 .LBB0_942
	s_waitcnt vmcnt(6)
	v_fmamk_f32 v5, v5, 0x3a800000, v231
	v_mul_f32_e32 v32, 0x4b800000, v5
	v_cmp_gt_f32_e32 vcc, s4, v5
	v_and_b32_e32 v33, 0xffff0000, v30
	s_lshl_b64 s[0:1], s[0:1], 10
	v_cndmask_b32_e32 v5, v5, v32, vcc
	v_rsq_f32_e32 v5, v5
	v_lshl_add_u64 v[34:35], s[0:1], 2, v[22:23]
	v_mul_f32_e32 v32, 0x45800000, v5
	v_cndmask_b32_e32 v36, v5, v32, vcc
	v_lshlrev_b32_e32 v32, 16, v30
	v_lshlrev_b32_e32 v30, 16, v31
	v_and_b32_e32 v31, 0xffff0000, v31
	v_pk_mul_f32 v[38:39], v[36:37], v[32:33] op_sel_hi:[0,1]
	v_pk_mul_f32 v[30:31], v[36:37], v[30:31] op_sel_hi:[0,1]
	v_pk_mul_f32 v[32:33], v[8:9], v[30:31]
	v_pk_mul_f32 v[30:31], v[6:7], v[38:39]
	global_store_dwordx4 v[34:35], v[30:33], off
	s_nop 1
	v_lshlrev_b32_e32 v30, 16, v28
	v_and_b32_e32 v31, 0xffff0000, v28
	v_lshlrev_b32_e32 v28, 16, v29
	v_and_b32_e32 v29, 0xffff0000, v29
	v_pk_mul_f32 v[32:33], v[36:37], v[30:31] op_sel_hi:[0,1]
	v_pk_mul_f32 v[28:29], v[36:37], v[28:29] op_sel_hi:[0,1]
	v_pk_mul_f32 v[30:31], v[12:13], v[28:29]
	v_pk_mul_f32 v[28:29], v[10:11], v[32:33]
	global_store_dwordx4 v[34:35], v[28:31], off offset:1024
	s_waitcnt vmcnt(7)
	s_nop 0
	v_lshlrev_b32_e32 v28, 16, v26
	v_and_b32_e32 v29, 0xffff0000, v26
	v_lshlrev_b32_e32 v26, 16, v27
	v_and_b32_e32 v27, 0xffff0000, v27
	v_pk_mul_f32 v[30:31], v[36:37], v[28:29] op_sel_hi:[0,1]
	v_pk_mul_f32 v[26:27], v[36:37], v[26:27] op_sel_hi:[0,1]
	v_pk_mul_f32 v[28:29], v[16:17], v[26:27]
	v_pk_mul_f32 v[26:27], v[14:15], v[30:31]
	global_store_dwordx4 v[34:35], v[26:29], off offset:2048
	s_waitcnt vmcnt(7)
	s_nop 0
	v_lshlrev_b32_e32 v26, 16, v24
	v_and_b32_e32 v27, 0xffff0000, v24
	v_lshlrev_b32_e32 v24, 16, v25
	v_and_b32_e32 v25, 0xffff0000, v25
	v_pk_mul_f32 v[28:29], v[36:37], v[26:27] op_sel_hi:[0,1]
	v_pk_mul_f32 v[24:25], v[36:37], v[24:25] op_sel_hi:[0,1]
	v_pk_mul_f32 v[26:27], v[20:21], v[24:25]
	v_pk_mul_f32 v[24:25], v[18:19], v[28:29]
	global_store_dwordx4 v[34:35], v[24:27], off offset:3072
	s_branch .LBB0_942

; __device__ __forceinline__ CvtItem cvt_decode(const Args& A, const int it) {
;     ...
;     const int kb = r / nblk, nb = r % nblk; c.k0 = 64 * kb; c.n0 = 32 * nb; c.spec = (kind == 2) && (c.n0 >= 3072);
;     c.W = W0; c.col0 = c.n0;
;     if (kind == 0) { const int pn = c.n0 >> 8, bj = (c.n0 >> 7) & 1, jj = c.n0 & 127; c.W = bj ? W1 : W0; c.col0 = pn * 128 + jj; }
;     if (kind == 2) c.col0 = (c.n0 < 1024) ? c.n0 : c.n0 + 16;
;     return c;
; }
; __device__ __forceinline__ void cvt_load(const CvtItem& c, const int lane, f32x4 (&vv)[8], float (&gv)[8]) {
;     const int kr = lane >> 3, nq = lane & 7;
;     if (!c.spec) {
; #pragma unroll
;         for (int i = 0; i < 8; ++i) vv[i] = *(const f32x4*)(c.W + (size_t)(c.k0 + 8 * i + kr) * c.Nsrc + c.col0 + 4 * nq);
; #pragma unroll
;         for (int i = 0; i < 8; ++i) gv[i] = c.gain ? c.gain[c.k0 + 8 * i + kr] : 1.0f;
.LBB0_975:
	s_sext_i32_i16 s0, s25
	v_cvt_f32_i32_e32 v2, s0
	s_sext_i32_i16 s1, s24
	v_cvt_f32_i32_e32 v3, s1
	s_xor_b32 s0, s1, s0
	s_waitcnt vmcnt(6)
	v_rcp_iflag_f32_e32 v5, v2
	s_ashr_i32 s0, s0, 30
	s_or_b32 s10, s0, 1
	s_waitcnt vmcnt(3) lgkmcnt(1)
	v_lshrrev_b32_e32 v20, 3, v86
	v_mul_f32_e32 v5, v3, v5
	v_trunc_f32_e32 v5, v5
	v_fma_f32 v3, -v5, v2, v3
	v_cvt_i32_f32_e32 v5, v5
	v_cmp_ge_f32_e64 s[0:1], |v3|, |v2|
	s_and_b64 s[0:1], s[0:1], exec
	s_cselect_b32 s0, s10, 0
	v_readfirstlane_b32 s1, v5
	s_add_i32 s0, s1, s0
	s_sext_i32_i16 s11, s0
	s_mul_i32 s0, s0, s25
	s_sub_i32 s20, s24, s0
	s_sext_i32_i16 s10, s20
	s_lshl_b32 s30, s10, 5
	s_cmpk_gt_i32 s10, 0x5f
	s_cselect_b64 s[0:1], -1, 0
	s_bitcmp0_b32 s20, 2
	s_cselect_b32 s20, s12, s16
	s_cselect_b32 s21, s13, s17
	s_and_b64 s[16:17], s[14:15], exec
	s_cselect_b32 s25, s21, s13
	s_cselect_b32 s24, s20, s12
	s_and_b64 s[20:21], s[18:19], s[0:1]
	v_lshlrev_b32_e32 v2, 2, v86
	s_lshl_b32 s34, s11, 6
	s_mov_b64 s[0:1], -1
	s_andn2_b64 vcc, exec, s[20:21]
	v_and_b32_e32 v14, 28, v2
	s_cbranch_vccz .LBB0_987
	s_or_b32 s0, s30, 16
	s_cmp_lt_i32 s10, 32
	s_cselect_b32 s11, s30, s0
	s_lshl_b32 s0, s10, 4
	s_and_b32 s0, s0, 0xffffff80
	s_and_b32 s1, s30, 0x60
	s_or_b32 s10, s0, s1
	s_and_b64 s[0:1], s[14:15], exec
	s_cselect_b32 s10, s10, s30
	s_and_b64 s[0:1], s[18:19], exec
	v_lshrrev_b32_e32 v87, 3, v86
	s_cselect_b32 s0, s11, s10
	v_and_b32_e32 v16, 28, v2
	v_or_b32_e32 v2, s34, v87
	s_waitcnt vmcnt(0) lgkmcnt(0)
	v_mul_hi_i32_i24_e32 v7, s3, v2
	v_mul_i32_i24_e32 v6, s3, v2
	s_ashr_i32 s1, s0, 31
	v_or_b32_e32 v3, 8, v2
	v_lshl_add_u64 v[6:7], v[6:7], 2, s[24:25]
	s_lshl_b64 s[0:1], s[0:1], 2
	v_mul_hi_i32_i24_e32 v11, s3, v3
	v_mul_i32_i24_e32 v10, s3, v3
	v_lshl_add_u64 v[6:7], v[6:7], 0, s[0:1]
	v_lshlrev_b32_e32 v8, 2, v16
	s_waitcnt lgkmcnt(0)
	v_mov_b32_e32 v9, v4
	v_lshl_add_u64 v[10:11], v[10:11], 2, s[24:25]
	v_lshl_add_u64 v[6:7], v[6:7], 0, v[8:9]
	v_lshl_add_u64 v[10:11], v[10:11], 0, s[0:1]
	v_or_b32_e32 v3, 16, v2
	v_lshl_add_u64 v[10:11], v[10:11], 0, v[8:9]
	global_load_dwordx4 v[22:25], v[6:7], off nt
	global_load_dwordx4 v[26:29], v[10:11], off nt
	v_mul_hi_i32_i24_e32 v7, s3, v3
	v_mul_i32_i24_e32 v6, s3, v3
	v_or_b32_e32 v3, 24, v2
	v_lshl_add_u64 v[6:7], v[6:7], 2, s[24:25]
	v_mul_hi_i32_i24_e32 v11, s3, v3
	v_mul_i32_i24_e32 v10, s3, v3
	v_lshl_add_u64 v[6:7], v[6:7], 0, s[0:1]
	v_lshl_add_u64 v[10:11], v[10:11], 2, s[24:25]
	v_lshl_add_u64 v[6:7], v[6:7], 0, v[8:9]
	v_lshl_add_u64 v[10:11], v[10:11], 0, s[0:1]
	v_or_b32_e32 v3, 32, v2
	v_lshl_add_u64 v[10:11], v[10:11], 0, v[8:9]
	global_load_dwordx4 v[30:33], v[6:7], off nt
	global_load_dwordx4 v[34:37], v[10:11], off nt
	v_mul_hi_i32_i24_e32 v7, s3, v3
	v_mul_i32_i24_e32 v6, s3, v3
	v_or_b32_e32 v3, 40, v2
	v_lshl_add_u64 v[6:7], v[6:7], 2, s[24:25]
	v_mul_hi_i32_i24_e32 v11, s3, v3
	v_mul_i32_i24_e32 v10, s3, v3
	v_lshl_add_u64 v[6:7], v[6:7], 0, s[0:1]
	v_lshl_add_u64 v[10:11], v[10:11], 2, s[24:25]
	v_lshl_add_u64 v[6:7], v[6:7], 0, v[8:9]
	v_lshl_add_u64 v[10:11], v[10:11], 0, s[0:1]
	v_or_b32_e32 v3, 48, v2
	v_lshl_add_u64 v[10:11], v[10:11], 0, v[8:9]
	global_load_dwordx4 v[38:41], v[6:7], off nt
	global_load_dwordx4 v[42:45], v[10:11], off nt
	v_mul_hi_i32_i24_e32 v7, s3, v3
	v_mul_i32_i24_e32 v6, s3, v3
	v_or_b32_e32 v3, 56, v2
	v_lshl_add_u64 v[6:7], v[6:7], 2, s[24:25]
	v_mul_hi_i32_i24_e32 v11, s3, v3
	v_mul_i32_i24_e32 v10, s3, v3
	v_lshl_add_u64 v[6:7], v[6:7], 0, s[0:1]
	v_lshl_add_u64 v[10:11], v[10:11], 2, s[24:25]
	v_lshl_add_u64 v[6:7], v[6:7], 0, v[8:9]
	v_lshl_add_u64 v[10:11], v[10:11], 0, s[0:1]
	v_lshl_add_u64 v[8:9], v[10:11], 0, v[8:9]
	global_load_dwordx4 v[46:49], v[6:7], off nt
	global_load_dwordx4 v[50:53], v[8:9], off nt
	v_ashrrev_i32_e32 v3, 31, v2
	s_cmp_lg_u64 s[8:9], 0
	s_cselect_b64 s[10:11], -1, 0
	s_cmp_eq_u64 s[8:9], 0
	v_lshl_add_u64 v[2:3], v[2:3], 2, s[8:9]
	s_cbranch_scc1 .LBB0_1123
	global_load_dword v6, v[2:3], off nt
	global_load_dword v7, v[2:3], off offset:32 nt
	v_cndmask_b32_e64 v5, 0, 1, s[10:11]
	v_cmp_ne_u32_e64 s[0:1], 1, v5
	s_andn2_b64 vcc, exec, s[10:11]
	s_cbranch_vccnz .LBB0_1124

; __device__ __forceinline__ CvtItem cvt_decode(const Args& A, const int it) {
;     ...
;     const int kb = r / nblk, nb = r % nblk; c.k0 = 64 * kb; c.n0 = 32 * nb; c.spec = (kind == 2) && (c.n0 >= 3072);
;     c.W = W0; c.col0 = c.n0;
;     if (kind == 0) { const int pn = c.n0 >> 8, bj = (c.n0 >> 7) & 1, jj = c.n0 & 127; c.W = bj ? W1 : W0; c.col0 = pn * 128 + jj; }
;     if (kind == 2) c.col0 = (c.n0 < 1024) ? c.n0 : c.n0 + 16;
;     return c;
; }
; __device__ __forceinline__ void cvt_load(const CvtItem& c, const int lane, f32x4 (&vv)[8], float (&gv)[8]) {
;     const int kr = lane >> 3, nq = lane & 7;
;     if (!c.spec) {
; #pragma unroll
;         for (int i = 0; i < 8; ++i) vv[i] = *(const f32x4*)(c.W + (size_t)(c.k0 + 8 * i + kr) * c.Nsrc + c.col0 + 4 * nq);
; #pragma unroll
;         for (int i = 0; i < 8; ++i) gv[i] = c.gain ? c.gain[c.k0 + 8 * i + kr] : 1.0f;
; __device__ __forceinline__ void convert_weights(const Args& A, LAS unsigned char* ldsl, int wave, int lane, const CvtList Lst, int gw, int NGW) {
;     ...
;         CvtItem nxt = cur; f32x4 vb[8]; float gb[8];
; #pragma unroll
;         for (int i = 0; i < 8; ++i) { vb[i] = va[i]; gb[i] = ga[i]; }
;         if (more) { nxt = cvt_decode(A, CVT_MAP(vn)); cvt_load(nxt, lane, vb, gb); }
.LBB0_1019:
	s_sext_i32_i16 s0, s37
	v_cvt_f32_i32_e32 v14, s0
	s_sext_i32_i16 s1, s36
	v_cvt_f32_i32_e32 v15, s1
	s_xor_b32 s0, s1, s0
	v_rcp_iflag_f32_e32 v16, v14
	s_ashr_i32 s0, s0, 30
	s_or_b32 s12, s0, 1
	v_mov_b64_e32 v[56:57], v[24:25]
	v_mul_f32_e32 v16, v15, v16
	v_trunc_f32_e32 v16, v16
	v_fma_f32 v15, -v16, v14, v15
	v_cvt_i32_f32_e32 v16, v16
	v_cmp_ge_f32_e64 s[0:1], |v15|, |v14|
	s_and_b64 s[0:1], s[0:1], exec
	s_cselect_b32 s0, s12, 0
	v_readfirstlane_b32 s1, v16
	s_add_i32 s0, s1, s0
	s_sext_i32_i16 s1, s0
	s_mul_i32 s0, s0, s37
	s_sub_i32 s27, s36, s0
	s_sext_i32_i16 s0, s27
	s_lshl_b32 s26, s0, 5
	s_cmpk_gt_i32 s0, 0x5f
	s_cselect_b64 s[12:13], -1, 0
	s_bitcmp0_b32 s27, 2
	s_cselect_b32 s27, s14, s18
	s_cselect_b32 s35, s15, s19
	s_and_b64 s[18:19], s[16:17], exec
	s_cselect_b32 s45, s35, s15
	s_cselect_b32 s44, s27, s14
	s_and_b64 s[12:13], s[22:23], s[12:13]
	v_mov_b64_e32 v[20:21], v[12:13]
	v_mov_b64_e32 v[60:61], v[28:29]
	v_mov_b64_e32 v[64:65], v[32:33]
	v_mov_b64_e32 v[68:69], v[36:37]
	v_mov_b64_e32 v[72:73], v[40:41]
	v_mov_b64_e32 v[76:77], v[44:45]
	v_mov_b64_e32 v[80:81], v[48:49]
	v_mov_b64_e32 v[84:85], v[52:53]
	s_lshl_b32 s14, s1, 6
	s_mov_b64 s[46:47], -1
	s_and_b64 vcc, exec, s[12:13]
	v_mov_b64_e32 v[18:19], v[10:11]
	v_mov_b64_e32 v[16:17], v[8:9]
	v_mov_b64_e32 v[14:15], v[6:7]
	v_mov_b64_e32 v[54:55], v[22:23]
	v_mov_b64_e32 v[58:59], v[26:27]
	v_mov_b64_e32 v[62:63], v[30:31]
	v_mov_b64_e32 v[66:67], v[34:35]
	v_mov_b64_e32 v[70:71], v[38:39]
	v_mov_b64_e32 v[74:75], v[42:43]
	v_mov_b64_e32 v[78:79], v[46:47]
	v_mov_b64_e32 v[82:83], v[50:51]
	s_cbranch_vccnz .LBB0_1033
	s_or_b32 s1, s26, 16
	s_cmp_lt_i32 s0, 32
	s_cselect_b32 s12, s26, s1
	s_lshl_b32 s0, s0, 4
	s_and_b32 s0, s0, 0xffffff80
	s_and_b32 s1, s26, 0x60
	s_or_b32 s13, s0, s1
	s_and_b64 s[0:1], s[16:17], exec
	s_cselect_b32 s13, s13, s26
	s_and_b64 s[0:1], s[22:23], exec
	s_cselect_b32 s0, s12, s13
	v_or_b32_e32 v14, s14, v87
	v_mul_hi_i32_i24_e32 v17, s49, v14
	v_mul_i32_i24_e32 v16, s49, v14
	s_ashr_i32 s1, s0, 31
	v_or_b32_e32 v15, 8, v14
	v_lshl_add_u64 v[16:17], v[16:17], 2, s[44:45]
	s_lshl_b64 s[0:1], s[0:1], 2
	v_mul_hi_i32_i24_e32 v19, s49, v15
	v_mul_i32_i24_e32 v18, s49, v15
	v_lshl_add_u64 v[16:17], v[16:17], 0, s[0:1]
	v_lshl_add_u64 v[18:19], v[18:19], 2, s[44:45]
	v_lshl_add_u64 v[16:17], v[16:17], 0, v[2:3]
	v_lshl_add_u64 v[18:19], v[18:19], 0, s[0:1]
	v_or_b32_e32 v15, 16, v14
	v_lshl_add_u64 v[18:19], v[18:19], 0, v[2:3]
	global_load_dwordx4 v[54:57], v[16:17], off nt
	global_load_dwordx4 v[58:61], v[18:19], off nt
	v_mul_hi_i32_i24_e32 v17, s49, v15
	v_mul_i32_i24_e32 v16, s49, v15
	v_or_b32_e32 v15, 24, v14
	v_lshl_add_u64 v[16:17], v[16:17], 2, s[44:45]
	v_mul_hi_i32_i24_e32 v19, s49, v15
	v_mul_i32_i24_e32 v18, s49, v15
	v_lshl_add_u64 v[16:17], v[16:17], 0, s[0:1]
	v_lshl_add_u64 v[18:19], v[18:19], 2, s[44:45]
	v_lshl_add_u64 v[16:17], v[16:17], 0, v[2:3]
	v_lshl_add_u64 v[18:19], v[18:19], 0, s[0:1]
	v_or_b32_e32 v15, 32, v14
	v_lshl_add_u64 v[18:19], v[18:19], 0, v[2:3]
	global_load_dwordx4 v[62:65], v[16:17], off nt
	global_load_dwordx4 v[66:69], v[18:19], off nt
	v_mul_hi_i32_i24_e32 v17, s49, v15
	v_mul_i32_i24_e32 v16, s49, v15
	v_or_b32_e32 v15, 40, v14
	v_lshl_add_u64 v[16:17], v[16:17], 2, s[44:45]
	v_mul_hi_i32_i24_e32 v19, s49, v15
	v_mul_i32_i24_e32 v18, s49, v15
	v_lshl_add_u64 v[16:17], v[16:17], 0, s[0:1]
	v_lshl_add_u64 v[18:19], v[18:19], 2, s[44:45]
	v_lshl_add_u64 v[16:17], v[16:17], 0, v[2:3]
	v_lshl_add_u64 v[18:19], v[18:19], 0, s[0:1]
	v_or_b32_e32 v15, 48, v14
	v_lshl_add_u64 v[18:19], v[18:19], 0, v[2:3]
	global_load_dwordx4 v[70:73], v[16:17], off nt
	global_load_dwordx4 v[74:77], v[18:19], off nt
	v_mul_hi_i32_i24_e32 v17, s49, v15
	v_mul_i32_i24_e32 v16, s49, v15
	v_or_b32_e32 v15, 56, v14
	v_lshl_add_u64 v[16:17], v[16:17], 2, s[44:45]
	v_mul_hi_i32_i24_e32 v19, s49, v15
	v_mul_i32_i24_e32 v18, s49, v15
	v_lshl_add_u64 v[16:17], v[16:17], 0, s[0:1]
	v_lshl_add_u64 v[18:19], v[18:19], 2, s[44:45]
	v_lshl_add_u64 v[16:17], v[16:17], 0, v[2:3]
	v_lshl_add_u64 v[18:19], v[18:19], 0, s[0:1]
	v_lshl_add_u64 v[18:19], v[18:19], 0, v[2:3]
	global_load_dwordx4 v[78:81], v[16:17], off nt
	global_load_dwordx4 v[82:85], v[18:19], off nt
	v_ashrrev_i32_e32 v15, 31, v14
	s_cmp_lg_u64 s[42:43], 0
	s_cselect_b64 s[12:13], -1, 0
	s_cmp_eq_u64 s[42:43], 0
	v_lshl_add_u64 v[90:91], v[14:15], 2, s[42:43]
	s_cbranch_scc1 .LBB0_1103
	global_load_dword v14, v[90:91], off nt
	global_load_dword v15, v[90:91], off offset:32 nt
	s_cbranch_execnz .LBB0_1023

; __device__ __forceinline__ void cvt_load(const CvtItem& c, const int lane, f32x4 (&vv)[8], float (&gv)[8]) {
;     ...
;         for (int i = 0; i < 8; ++i) gv[i] = c.gain ? c.gain[c.k0 + 8 * i + kr] : 1.0f;
.LBB0_1023:
	v_cndmask_b32_e64 v16, 0, 1, s[12:13]
	v_cmp_ne_u32_e64 s[0:1], 1, v16
	s_andn2_b64 vcc, exec, s[12:13]
	s_cbranch_vccnz .LBB0_1104
	global_load_dword v16, v[90:91], off offset:64 nt
	global_load_dword v17, v[90:91], off offset:96 nt
	s_cbranch_execnz .LBB0_1026

; __device__ __forceinline__ void cvt_load(const CvtItem& c, const int lane, f32x4 (&vv)[8], float (&gv)[8]) {
;     ...
;         for (int i = 0; i < 8; ++i) gv[i] = c.gain ? c.gain[c.k0 + 8 * i + kr] : 1.0f;
.LBB0_1026:
	s_and_b64 vcc, exec, s[0:1]
	s_cbranch_vccnz .LBB0_1105
	global_load_dword v18, v[90:91], off offset:128 nt
	global_load_dword v19, v[90:91], off offset:160 nt
	s_cbranch_execnz .LBB0_1029

; __device__ __forceinline__ void cvt_load(const CvtItem& c, const int lane, f32x4 (&vv)[8], float (&gv)[8]) {
;     ...
;         for (int i = 0; i < 8; ++i) gv[i] = c.gain ? c.gain[c.k0 + 8 * i + kr] : 1.0f;
.LBB0_1029:
	s_and_b64 vcc, exec, s[0:1]
	s_cbranch_vccnz .LBB0_1106
	global_load_dword v20, v[90:91], off offset:192 nt
	global_load_dword v21, v[90:91], off offset:224 nt
	s_cbranch_execnz .LBB0_1032

; __device__ __forceinline__ void cvt_finish(const CvtItem& c, const int lane, LAS float* scr, const f32x4 (&vv)[8], const float (&gv)[8]) {
;     ...
;         const int np = c.n0 + (lane & 31);
;         int col = 0; bool valid = true;
;         if (np < 3088) col = 1024 + (np - 3072); else if (np < NIN) col = np; else valid = false;
;         float ev[32];
; #pragma unroll
;         for (int i = 0; i < 32; ++i) ev[i] = c.W[(size_t)(c.k0 + 2 * i + (lane >> 5)) * c.Nsrc + col];
.LBB0_1035:
	s_andn2_b64 vcc, exec, s[0:1]
	s_cbranch_vccnz .LBB0_1101
	v_add_u32_e32 v89, s30, v96
	s_movk_i32 s0, 0xc10
	s_movk_i32 s12, 0xc14
	v_cmp_gt_i32_e32 vcc, s0, v89
	v_cmp_gt_u32_e64 s[0:1], s12, v89
	v_add_u32_e32 v90, 0xfffff800, v89
	s_cmp_lg_u64 s[8:9], 0
	v_cndmask_b32_e64 v91, 0, v89, s[0:1]
	v_cndmask_b32_e32 v92, v91, v90, vcc
	v_add_u32_e32 v90, s34, v97
	v_mad_u64_u32 v[104:105], s[0:1], v90, s3, 0
	v_ashrrev_i32_e32 v91, 31, v90
	v_mov_b32_e32 v106, v105
	v_ashrrev_i32_e32 v93, 31, v92
	v_mad_u64_u32 v[106:107], s[0:1], v91, s3, v[106:107]
	v_lshl_add_u64 v[92:93], v[92:93], 2, s[24:25]
	v_mov_b32_e32 v105, v106
	v_lshl_add_u64 v[104:105], v[104:105], 2, v[92:93]
	global_load_dword v110, v[104:105], off nt
	v_add_u32_e32 v104, 2, v90
	v_ashrrev_i32_e32 v107, 31, v104
	v_mad_u64_u32 v[104:105], s[0:1], v104, s3, 0
	v_mov_b32_e32 v106, v105
	v_mad_u64_u32 v[106:107], s[0:1], v107, s3, v[106:107]
	v_mov_b32_e32 v105, v106
	v_lshl_add_u64 v[104:105], v[104:105], 2, v[92:93]
	global_load_dword v104, v[104:105], off nt
	v_add_u32_e32 v105, 4, v90
	v_mad_u64_u32 v[106:107], s[0:1], v105, s3, 0
	v_ashrrev_i32_e32 v109, 31, v105
	v_mov_b32_e32 v108, v107
	v_mad_u64_u32 v[108:109], s[0:1], v109, s3, v[108:109]
	v_mov_b32_e32 v107, v108
	v_lshl_add_u64 v[106:107], v[106:107], 2, v[92:93]
	global_load_dword v105, v[106:107], off nt
	v_add_u32_e32 v106, 6, v90
	v_ashrrev_i32_e32 v109, 31, v106
	v_mad_u64_u32 v[106:107], s[0:1], v106, s3, 0
	v_mov_b32_e32 v108, v107
	v_mad_u64_u32 v[108:109], s[0:1], v109, s3, v[108:109]
	v_mov_b32_e32 v107, v108
	v_lshl_add_u64 v[106:107], v[106:107], 2, v[92:93]
	global_load_dword v106, v[106:107], off nt
	v_add_u32_e32 v107, 8, v90
	v_mad_u64_u32 v[108:109], s[0:1], v107, s3, 0
	v_ashrrev_i32_e32 v111, 31, v107
	v_mov_b32_e32 v112, v109
	v_mad_u64_u32 v[112:113], s[0:1], v111, s3, v[112:113]
	v_mov_b32_e32 v109, v112
	v_lshl_add_u64 v[108:109], v[108:109], 2, v[92:93]
	global_load_dword v107, v[108:109], off nt
	v_add_u32_e32 v108, 10, v90
	v_ashrrev_i32_e32 v111, 31, v108
	v_mad_u64_u32 v[108:109], s[0:1], v108, s3, 0
	v_mov_b32_e32 v112, v109
	v_mad_u64_u32 v[112:113], s[0:1], v111, s3, v[112:113]
	v_mov_b32_e32 v109, v112
	v_lshl_add_u64 v[108:109], v[108:109], 2, v[92:93]
	global_load_dword v108, v[108:109], off nt
	v_add_u32_e32 v109, 12, v90
	v_mad_u64_u32 v[112:113], s[0:1], v109, s3, 0
	v_ashrrev_i32_e32 v111, 31, v109
	v_mov_b32_e32 v114, v113
	v_mad_u64_u32 v[114:115], s[0:1], v111, s3, v[114:115]
	v_mov_b32_e32 v113, v114
	v_lshl_add_u64 v[112:113], v[112:113], 2, v[92:93]
	v_add_u32_e32 v111, 14, v90
	global_load_dword v109, v[112:113], off nt
	v_mad_u64_u32 v[112:113], s[0:1], v111, s3, 0
	v_ashrrev_i32_e32 v115, 31, v111
	v_mov_b32_e32 v114, v113
	v_mad_u64_u32 v[114:115], s[0:1], v115, s3, v[114:115]
	v_mov_b32_e32 v113, v114
	v_lshl_add_u64 v[112:113], v[112:113], 2, v[92:93]
	v_add_u32_e32 v111, 16, v90
	global_load_dword v118, v[112:113], off nt
	v_mad_u64_u32 v[112:113], s[0:1], v111, s3, 0
	v_ashrrev_i32_e32 v115, 31, v111
	v_mov_b32_e32 v114, v113
	v_mad_u64_u32 v[114:115], s[0:1], v115, s3, v[114:115]
	v_mov_b32_e32 v113, v114
	v_lshl_add_u64 v[112:113], v[112:113], 2, v[92:93]
	global_load_dword v111, v[112:113], off nt
	v_add_u32_e32 v112, 18, v90
	v_ashrrev_i32_e32 v115, 31, v112
	v_mad_u64_u32 v[112:113], s[0:1], v112, s3, 0
	v_mov_b32_e32 v114, v113
	v_mad_u64_u32 v[114:115], s[0:1], v115, s3, v[114:115]
	v_mov_b32_e32 v113, v114
	v_lshl_add_u64 v[112:113], v[112:113], 2, v[92:93]
	global_load_dword v112, v[112:113], off nt
	v_add_u32_e32 v113, 20, v90
	v_mad_u64_u32 v[114:115], s[0:1], v113, s3, 0
	v_ashrrev_i32_e32 v117, 31, v113
	v_mov_b32_e32 v116, v115
	v_mad_u64_u32 v[116:117], s[0:1], v117, s3, v[116:117]
	v_mov_b32_e32 v115, v116
	v_lshl_add_u64 v[114:115], v[114:115], 2, v[92:93]
	global_load_dword v113, v[114:115], off nt
	v_add_u32_e32 v114, 22, v90
	v_ashrrev_i32_e32 v117, 31, v114
	v_mad_u64_u32 v[114:115], s[0:1], v114, s3, 0
	v_mov_b32_e32 v116, v115
	v_mad_u64_u32 v[116:117], s[0:1], v117, s3, v[116:117]
	v_mov_b32_e32 v115, v116
	v_lshl_add_u64 v[114:115], v[114:115], 2, v[92:93]
	global_load_dword v114, v[114:115], off nt
	v_add_u32_e32 v115, 24, v90
	v_mad_u64_u32 v[116:117], s[0:1], v115, s3, 0
	v_ashrrev_i32_e32 v119, 31, v115
	v_mov_b32_e32 v120, v117
	v_mad_u64_u32 v[120:121], s[0:1], v119, s3, v[120:121]
	v_mov_b32_e32 v117, v120
	v_lshl_add_u64 v[116:117], v[116:117], 2, v[92:93]
	global_load_dword v115, v[116:117], off nt
	v_add_u32_e32 v116, 26, v90
	v_ashrrev_i32_e32 v119, 31, v116
	v_mad_u64_u32 v[116:117], s[0:1], v116, s3, 0
	v_mov_b32_e32 v120, v117
	v_mad_u64_u32 v[120:121], s[0:1], v119, s3, v[120:121]
	v_mov_b32_e32 v117, v120
	v_lshl_add_u64 v[116:117], v[116:117], 2, v[92:93]
	global_load_dword v116, v[116:117], off nt
	v_add_u32_e32 v117, 28, v90
	v_mad_u64_u32 v[120:121], s[0:1], v117, s3, 0
	v_ashrrev_i32_e32 v119, 31, v117
	v_mov_b32_e32 v122, v121
	v_mad_u64_u32 v[122:123], s[0:1], v119, s3, v[122:123]
	v_mov_b32_e32 v121, v122
	v_lshl_add_u64 v[120:121], v[120:121], 2, v[92:93]
	v_add_u32_e32 v119, 30, v90
	global_load_dword v117, v[120:121], off nt
	v_mad_u64_u32 v[120:121], s[0:1], v119, s3, 0
	v_ashrrev_i32_e32 v123, 31, v119
	v_mov_b32_e32 v122, v121
	v_mad_u64_u32 v[122:123], s[0:1], v123, s3, v[122:123]
	v_mov_b32_e32 v121, v122
	v_lshl_add_u64 v[120:121], v[120:121], 2, v[92:93]
	v_add_u32_e32 v119, 32, v90
	global_load_dword v126, v[120:121], off nt
	v_mad_u64_u32 v[120:121], s[0:1], v119, s3, 0
	v_ashrrev_i32_e32 v123, 31, v119
	v_mov_b32_e32 v122, v121
	v_mad_u64_u32 v[122:123], s[0:1], v123, s3, v[122:123]
; __device__ __forceinline__ void cvt_finish(const CvtItem& c, const int lane, LAS float* scr, const f32x4 (&vv)[8], const float (&gv)[8]) {
;     ...
;         for (int i = 0; i < 32; ++i) ev[i] = c.W[(size_t)(c.k0 + 2 * i + (lane >> 5)) * c.Nsrc + col];
; #pragma unroll
;         for (int i = 0; i < 32; ++i) { const int kk = 2 * i + (lane >> 5); float v = valid ? ev[i] : 0.f; if (c.gain) v *= c.gain[c.k0 + kk]; scr[kk * 33 + (lane & 31)] = v; }
	v_mov_b32_e32 v121, v122
	v_lshl_add_u64 v[120:121], v[120:121], 2, v[92:93]
	global_load_dword v119, v[120:121], off nt
	v_add_u32_e32 v120, 34, v90
	v_ashrrev_i32_e32 v123, 31, v120
	v_mad_u64_u32 v[120:121], s[0:1], v120, s3, 0
	v_mov_b32_e32 v122, v121
	v_mad_u64_u32 v[122:123], s[0:1], v123, s3, v[122:123]
	v_mov_b32_e32 v121, v122
	v_lshl_add_u64 v[120:121], v[120:121], 2, v[92:93]
	global_load_dword v120, v[120:121], off nt
	v_add_u32_e32 v121, 36, v90
	v_mad_u64_u32 v[122:123], s[0:1], v121, s3, 0
	v_ashrrev_i32_e32 v125, 31, v121
	v_mov_b32_e32 v124, v123
	v_mad_u64_u32 v[124:125], s[0:1], v125, s3, v[124:125]
	v_mov_b32_e32 v123, v124
	v_lshl_add_u64 v[122:123], v[122:123], 2, v[92:93]
	global_load_dword v121, v[122:123], off nt
	v_add_u32_e32 v122, 38, v90
	v_ashrrev_i32_e32 v125, 31, v122
	v_mad_u64_u32 v[122:123], s[0:1], v122, s3, 0
	v_mov_b32_e32 v124, v123
	v_mad_u64_u32 v[124:125], s[0:1], v125, s3, v[124:125]
	v_mov_b32_e32 v123, v124
	v_lshl_add_u64 v[122:123], v[122:123], 2, v[92:93]
	global_load_dword v122, v[122:123], off nt
	v_add_u32_e32 v123, 40, v90
	v_mad_u64_u32 v[124:125], s[0:1], v123, s3, 0
	v_ashrrev_i32_e32 v127, 31, v123
	v_mov_b32_e32 v128, v125
	v_mad_u64_u32 v[128:129], s[0:1], v127, s3, v[128:129]
	v_mov_b32_e32 v125, v128
	v_lshl_add_u64 v[124:125], v[124:125], 2, v[92:93]
	global_load_dword v123, v[124:125], off nt
	v_add_u32_e32 v124, 42, v90
	v_ashrrev_i32_e32 v127, 31, v124
	v_mad_u64_u32 v[124:125], s[0:1], v124, s3, 0
	v_mov_b32_e32 v128, v125
	v_mad_u64_u32 v[128:129], s[0:1], v127, s3, v[128:129]
	v_mov_b32_e32 v125, v128
	v_lshl_add_u64 v[124:125], v[124:125], 2, v[92:93]
	global_load_dword v124, v[124:125], off nt
	v_add_u32_e32 v125, 44, v90
	v_mad_u64_u32 v[128:129], s[0:1], v125, s3, 0
	v_ashrrev_i32_e32 v127, 31, v125
	v_mov_b32_e32 v130, v129
	v_mad_u64_u32 v[130:131], s[0:1], v127, s3, v[130:131]
	v_mov_b32_e32 v129, v130
	v_lshl_add_u64 v[128:129], v[128:129], 2, v[92:93]
	v_add_u32_e32 v127, 46, v90
	global_load_dword v125, v[128:129], off nt
	v_mad_u64_u32 v[128:129], s[0:1], v127, s3, 0
	v_ashrrev_i32_e32 v131, 31, v127
	v_mov_b32_e32 v130, v129
	v_mad_u64_u32 v[130:131], s[0:1], v131, s3, v[130:131]
	v_mov_b32_e32 v129, v130
	v_lshl_add_u64 v[128:129], v[128:129], 2, v[92:93]
	v_add_u32_e32 v127, 48, v90
	global_load_dword v134, v[128:129], off nt
	v_mad_u64_u32 v[128:129], s[0:1], v127, s3, 0
	v_ashrrev_i32_e32 v131, 31, v127
	v_mov_b32_e32 v130, v129
	v_mad_u64_u32 v[130:131], s[0:1], v131, s3, v[130:131]
	v_mov_b32_e32 v129, v130
	v_lshl_add_u64 v[128:129], v[128:129], 2, v[92:93]
	global_load_dword v127, v[128:129], off nt
	v_add_u32_e32 v128, 50, v90
	v_ashrrev_i32_e32 v131, 31, v128
	v_mad_u64_u32 v[128:129], s[0:1], v128, s3, 0
	v_mov_b32_e32 v130, v129
	v_mad_u64_u32 v[130:131], s[0:1], v131, s3, v[130:131]
	v_mov_b32_e32 v129, v130
	v_lshl_add_u64 v[128:129], v[128:129], 2, v[92:93]
	global_load_dword v128, v[128:129], off nt
	v_add_u32_e32 v129, 52, v90
	v_mad_u64_u32 v[130:131], s[0:1], v129, s3, 0
	v_ashrrev_i32_e32 v133, 31, v129
	v_mov_b32_e32 v132, v131
	v_mad_u64_u32 v[132:133], s[0:1], v133, s3, v[132:133]
	v_mov_b32_e32 v131, v132
	v_lshl_add_u64 v[130:131], v[130:131], 2, v[92:93]
	global_load_dword v129, v[130:131], off nt
	v_add_u32_e32 v130, 54, v90
	v_ashrrev_i32_e32 v133, 31, v130
	v_mad_u64_u32 v[130:131], s[0:1], v130, s3, 0
	v_mov_b32_e32 v132, v131
	v_mad_u64_u32 v[132:133], s[0:1], v133, s3, v[132:133]
	v_mov_b32_e32 v131, v132
	v_lshl_add_u64 v[130:131], v[130:131], 2, v[92:93]
	global_load_dword v130, v[130:131], off nt
	v_add_u32_e32 v131, 56, v90
	v_mad_u64_u32 v[132:133], s[0:1], v131, s3, 0
	v_ashrrev_i32_e32 v135, 31, v131
	v_mov_b32_e32 v136, v133
	v_mad_u64_u32 v[136:137], s[0:1], v135, s3, v[136:137]
	v_mov_b32_e32 v133, v136
	v_lshl_add_u64 v[132:133], v[132:133], 2, v[92:93]
	global_load_dword v131, v[132:133], off nt
	v_add_u32_e32 v132, 58, v90
	v_ashrrev_i32_e32 v135, 31, v132
	v_mad_u64_u32 v[132:133], s[0:1], v132, s3, 0
	v_mov_b32_e32 v136, v133
	v_mad_u64_u32 v[136:137], s[0:1], v135, s3, v[136:137]
	v_mov_b32_e32 v133, v136
	v_lshl_add_u64 v[132:133], v[132:133], 2, v[92:93]
	global_load_dword v132, v[132:133], off nt
	v_add_u32_e32 v133, 60, v90
	v_mad_u64_u32 v[136:137], s[0:1], v133, s3, 0
	v_ashrrev_i32_e32 v135, 31, v133
	v_mov_b32_e32 v138, v137
	v_mad_u64_u32 v[138:139], s[0:1], v135, s3, v[138:139]
	v_mov_b32_e32 v137, v138
	v_lshl_add_u64 v[136:137], v[136:137], 2, v[92:93]
	v_add_u32_e32 v135, 62, v90
	global_load_dword v133, v[136:137], off nt
	v_mad_u64_u32 v[136:137], s[0:1], v135, s3, 0
	v_ashrrev_i32_e32 v139, 31, v135
	v_mov_b32_e32 v138, v137
	v_mad_u64_u32 v[138:139], s[0:1], v139, s3, v[138:139]
	v_mov_b32_e32 v137, v138
	v_lshl_add_u64 v[92:93], v[136:137], 2, v[92:93]
	global_load_dword v92, v[92:93], off nt
	v_cmp_gt_i32_e64 s[0:1], s12, v89
	s_cselect_b64 s[12:13], -1, 0
	s_cmp_eq_u64 s[8:9], 0
	s_waitcnt vmcnt(31)
	v_cndmask_b32_e64 v89, 0, v110, s[0:1]
	v_lshl_add_u64 v[90:91], v[90:91], 2, s[8:9]
	s_cbranch_scc1 .LBB0_1038
	global_load_dword v93, v[90:91], off nt
	s_waitcnt vmcnt(0)
	v_mul_f32_e32 v89, v89, v93
.LBB0_1038:
	ds_write_b32 v103, v89
	v_cndmask_b32_e64 v89, 0, 1, s[12:13]
	v_cmp_ne_u32_e64 s[36:37], 1, v89
	s_andn2_b64 vcc, exec, s[12:13]
	s_waitcnt vmcnt(30)
	v_cndmask_b32_e64 v89, 0, v104, s[0:1]
	s_cbranch_vccnz .LBB0_1040
	global_load_dword v93, v[90:91], off offset:8 nt
	s_waitcnt vmcnt(0)
	v_mul_f32_e32 v89, v89, v93
.LBB0_1040:
	ds_write_b32 v103, v89 offset:264
	s_and_b64 vcc, exec, s[36:37]
	s_waitcnt vmcnt(29)
	v_cndmask_b32_e64 v89, 0, v105, s[0:1]
	s_cbranch_vccnz .LBB0_1042
	global_load_dword v93, v[90:91], off offset:16 nt
	s_waitcnt vmcnt(0)
	v_mul_f32_e32 v89, v89, v93
; __device__ __forceinline__ void cvt_finish(const CvtItem& c, const int lane, LAS float* scr, const f32x4 (&vv)[8], const float (&gv)[8]) {
;     ...
;         for (int i = 0; i < 32; ++i) { const int kk = 2 * i + (lane >> 5); float v = valid ? ev[i] : 0.f; if (c.gain) v *= c.gain[c.k0 + kk]; scr[kk * 33 + (lane & 31)] = v; }
.LBB0_1042:
	ds_write_b32 v103, v89 offset:528
	s_and_b64 vcc, exec, s[36:37]
	s_waitcnt vmcnt(28)
	v_cndmask_b32_e64 v89, 0, v106, s[0:1]
	s_cbranch_vccnz .LBB0_1044
	global_load_dword v93, v[90:91], off offset:24 nt
	s_waitcnt vmcnt(0)
	v_mul_f32_e32 v89, v89, v93
.LBB0_1044:
	ds_write_b32 v103, v89 offset:792
	s_and_b64 vcc, exec, s[36:37]
	s_waitcnt vmcnt(27)
	v_cndmask_b32_e64 v89, 0, v107, s[0:1]
	s_cbranch_vccnz .LBB0_1046
	global_load_dword v93, v[90:91], off offset:32 nt
	s_waitcnt vmcnt(0)
	v_mul_f32_e32 v89, v89, v93
.LBB0_1046:
	ds_write_b32 v103, v89 offset:1056
	s_and_b64 vcc, exec, s[36:37]
	s_waitcnt vmcnt(26)
	v_cndmask_b32_e64 v89, 0, v108, s[0:1]
	s_cbranch_vccnz .LBB0_1048
	global_load_dword v93, v[90:91], off offset:40 nt
	s_waitcnt vmcnt(0)
	v_mul_f32_e32 v89, v89, v93
.LBB0_1048:
	ds_write_b32 v103, v89 offset:1320
	s_and_b64 vcc, exec, s[36:37]
	s_waitcnt vmcnt(25)
	v_cndmask_b32_e64 v89, 0, v109, s[0:1]
	s_cbranch_vccnz .LBB0_1050
	global_load_dword v93, v[90:91], off offset:48 nt
	s_waitcnt vmcnt(0)
	v_mul_f32_e32 v89, v89, v93
.LBB0_1050:
	ds_write_b32 v103, v89 offset:1584
	s_and_b64 vcc, exec, s[36:37]
	s_waitcnt vmcnt(24)
	v_cndmask_b32_e64 v89, 0, v118, s[0:1]
	s_cbranch_vccnz .LBB0_1052
	global_load_dword v93, v[90:91], off offset:56 nt
	s_waitcnt vmcnt(0)
	v_mul_f32_e32 v89, v89, v93
.LBB0_1052:
	ds_write_b32 v103, v89 offset:1848
	s_and_b64 vcc, exec, s[36:37]
	s_waitcnt vmcnt(23)
	v_cndmask_b32_e64 v89, 0, v111, s[0:1]
	s_cbranch_vccnz .LBB0_1054
	global_load_dword v93, v[90:91], off offset:64 nt
	s_waitcnt vmcnt(0)
	v_mul_f32_e32 v89, v89, v93
.LBB0_1054:
	ds_write_b32 v103, v89 offset:2112
	s_and_b64 vcc, exec, s[36:37]
	s_waitcnt vmcnt(22)
	v_cndmask_b32_e64 v89, 0, v112, s[0:1]
	s_cbranch_vccnz .LBB0_1056
	global_load_dword v93, v[90:91], off offset:72 nt
	s_waitcnt vmcnt(0)
	v_mul_f32_e32 v89, v89, v93
.LBB0_1056:
	ds_write_b32 v103, v89 offset:2376
	s_and_b64 vcc, exec, s[36:37]
	s_waitcnt vmcnt(21)
	v_cndmask_b32_e64 v89, 0, v113, s[0:1]
	s_cbranch_vccnz .LBB0_1058
	global_load_dword v93, v[90:91], off offset:80 nt
	s_waitcnt vmcnt(0)
	v_mul_f32_e32 v89, v89, v93
.LBB0_1058:
	ds_write_b32 v103, v89 offset:2640
	s_and_b64 vcc, exec, s[36:37]
	s_waitcnt vmcnt(20)
	v_cndmask_b32_e64 v89, 0, v114, s[0:1]
	s_cbranch_vccnz .LBB0_1060
	global_load_dword v93, v[90:91], off offset:88 nt
	s_waitcnt vmcnt(0)
	v_mul_f32_e32 v89, v89, v93
.LBB0_1060:
	ds_write_b32 v103, v89 offset:2904
	s_and_b64 vcc, exec, s[36:37]
	s_waitcnt vmcnt(19)
	v_cndmask_b32_e64 v89, 0, v115, s[0:1]
	s_cbranch_vccnz .LBB0_1062
	global_load_dword v93, v[90:91], off offset:96 nt
	s_waitcnt vmcnt(0)
	v_mul_f32_e32 v89, v89, v93
.LBB0_1062:
	ds_write_b32 v103, v89 offset:3168
	s_and_b64 vcc, exec, s[36:37]
	s_waitcnt vmcnt(18)
	v_cndmask_b32_e64 v89, 0, v116, s[0:1]
	s_cbranch_vccnz .LBB0_1064
	global_load_dword v93, v[90:91], off offset:104 nt
	s_waitcnt vmcnt(0)
	v_mul_f32_e32 v89, v89, v93
.LBB0_1064:
	ds_write_b32 v103, v89 offset:3432
	s_and_b64 vcc, exec, s[36:37]
	s_waitcnt vmcnt(17)
	v_cndmask_b32_e64 v89, 0, v117, s[0:1]
	s_cbranch_vccnz .LBB0_1066
	global_load_dword v93, v[90:91], off offset:112 nt
	s_waitcnt vmcnt(0)
	v_mul_f32_e32 v89, v89, v93
.LBB0_1066:
	ds_write_b32 v103, v89 offset:3696
	s_and_b64 vcc, exec, s[36:37]
	s_waitcnt vmcnt(16)
	v_cndmask_b32_e64 v89, 0, v126, s[0:1]
	s_cbranch_vccnz .LBB0_1068
	global_load_dword v93, v[90:91], off offset:120 nt
	s_waitcnt vmcnt(0)
	v_mul_f32_e32 v89, v89, v93
.LBB0_1068:
	ds_write_b32 v103, v89 offset:3960
	s_and_b64 vcc, exec, s[36:37]
	s_waitcnt vmcnt(15)
	v_cndmask_b32_e64 v89, 0, v119, s[0:1]
	s_cbranch_vccnz .LBB0_1070
	global_load_dword v93, v[90:91], off offset:128 nt
	s_waitcnt vmcnt(0)
	v_mul_f32_e32 v89, v89, v93
.LBB0_1070:
	ds_write_b32 v103, v89 offset:4224
	s_and_b64 vcc, exec, s[36:37]
	s_waitcnt vmcnt(14)
	v_cndmask_b32_e64 v89, 0, v120, s[0:1]
	s_cbranch_vccnz .LBB0_1072
	global_load_dword v93, v[90:91], off offset:136 nt
	s_waitcnt vmcnt(0)
	v_mul_f32_e32 v89, v89, v93
; __device__ __forceinline__ void cvt_finish(const CvtItem& c, const int lane, LAS float* scr, const f32x4 (&vv)[8], const float (&gv)[8]) {
;     ...
;         for (int i = 0; i < 32; ++i) { const int kk = 2 * i + (lane >> 5); float v = valid ? ev[i] : 0.f; if (c.gain) v *= c.gain[c.k0 + kk]; scr[kk * 33 + (lane & 31)] = v; }
.LBB0_1072:
	ds_write_b32 v103, v89 offset:4488
	s_and_b64 vcc, exec, s[36:37]
	s_waitcnt vmcnt(13)
	v_cndmask_b32_e64 v89, 0, v121, s[0:1]
	s_cbranch_vccnz .LBB0_1074
	global_load_dword v93, v[90:91], off offset:144 nt
	s_waitcnt vmcnt(0)
	v_mul_f32_e32 v89, v89, v93
.LBB0_1074:
	ds_write_b32 v103, v89 offset:4752
	s_and_b64 vcc, exec, s[36:37]
	s_waitcnt vmcnt(12)
	v_cndmask_b32_e64 v89, 0, v122, s[0:1]
	s_cbranch_vccnz .LBB0_1076
	global_load_dword v93, v[90:91], off offset:152 nt
	s_waitcnt vmcnt(0)
	v_mul_f32_e32 v89, v89, v93
.LBB0_1076:
	ds_write_b32 v103, v89 offset:5016
	s_and_b64 vcc, exec, s[36:37]
	s_waitcnt vmcnt(11)
	v_cndmask_b32_e64 v89, 0, v123, s[0:1]
	s_cbranch_vccnz .LBB0_1078
	global_load_dword v93, v[90:91], off offset:160 nt
	s_waitcnt vmcnt(0)
	v_mul_f32_e32 v89, v89, v93
.LBB0_1078:
	ds_write_b32 v103, v89 offset:5280
	s_and_b64 vcc, exec, s[36:37]
	s_waitcnt vmcnt(10)
	v_cndmask_b32_e64 v89, 0, v124, s[0:1]
	s_cbranch_vccnz .LBB0_1080
	global_load_dword v93, v[90:91], off offset:168 nt
	s_waitcnt vmcnt(0)
	v_mul_f32_e32 v89, v89, v93
.LBB0_1080:
	ds_write_b32 v103, v89 offset:5544
	s_and_b64 vcc, exec, s[36:37]
	s_waitcnt vmcnt(9)
	v_cndmask_b32_e64 v89, 0, v125, s[0:1]
	s_cbranch_vccnz .LBB0_1082
	global_load_dword v93, v[90:91], off offset:176 nt
	s_waitcnt vmcnt(0)
	v_mul_f32_e32 v89, v89, v93
.LBB0_1082:
	ds_write_b32 v103, v89 offset:5808
	s_and_b64 vcc, exec, s[36:37]
	s_waitcnt vmcnt(8)
	v_cndmask_b32_e64 v89, 0, v134, s[0:1]
	s_cbranch_vccnz .LBB0_1084
	global_load_dword v93, v[90:91], off offset:184 nt
	s_waitcnt vmcnt(0)
	v_mul_f32_e32 v89, v89, v93
.LBB0_1084:
	ds_write_b32 v103, v89 offset:6072
	s_and_b64 vcc, exec, s[36:37]
	s_waitcnt vmcnt(7)
	v_cndmask_b32_e64 v89, 0, v127, s[0:1]
	s_cbranch_vccnz .LBB0_1086
	global_load_dword v93, v[90:91], off offset:192 nt
	s_waitcnt vmcnt(0)
	v_mul_f32_e32 v89, v89, v93
.LBB0_1086:
	ds_write_b32 v103, v89 offset:6336
	s_and_b64 vcc, exec, s[36:37]
	s_waitcnt vmcnt(6)
	v_cndmask_b32_e64 v89, 0, v128, s[0:1]
	s_cbranch_vccnz .LBB0_1088
	global_load_dword v93, v[90:91], off offset:200 nt
	s_waitcnt vmcnt(0)
	v_mul_f32_e32 v89, v89, v93
.LBB0_1088:
	ds_write_b32 v103, v89 offset:6600
	s_and_b64 vcc, exec, s[36:37]
	s_waitcnt vmcnt(5)
	v_cndmask_b32_e64 v89, 0, v129, s[0:1]
	s_cbranch_vccnz .LBB0_1090
	global_load_dword v93, v[90:91], off offset:208 nt
	s_waitcnt vmcnt(0)
	v_mul_f32_e32 v89, v89, v93
.LBB0_1090:
	ds_write_b32 v103, v89 offset:6864
	s_and_b64 vcc, exec, s[36:37]
	s_waitcnt vmcnt(4)
	v_cndmask_b32_e64 v89, 0, v130, s[0:1]
	s_cbranch_vccnz .LBB0_1092
	global_load_dword v93, v[90:91], off offset:216 nt
	s_waitcnt vmcnt(0)
	v_mul_f32_e32 v89, v89, v93
.LBB0_1092:
	ds_write_b32 v103, v89 offset:7128
	s_and_b64 vcc, exec, s[36:37]
	s_waitcnt vmcnt(3)
	v_cndmask_b32_e64 v89, 0, v131, s[0:1]
	s_cbranch_vccnz .LBB0_1094
	global_load_dword v93, v[90:91], off offset:224 nt
	s_waitcnt vmcnt(0)
	v_mul_f32_e32 v89, v89, v93
.LBB0_1094:
	ds_write_b32 v103, v89 offset:7392
	s_and_b64 vcc, exec, s[36:37]
	s_waitcnt vmcnt(2)
	v_cndmask_b32_e64 v89, 0, v132, s[0:1]
	s_cbranch_vccnz .LBB0_1096
	global_load_dword v93, v[90:91], off offset:232 nt
	s_waitcnt vmcnt(0)
	v_mul_f32_e32 v89, v89, v93
.LBB0_1096:
	ds_write_b32 v103, v89 offset:7656
	s_and_b64 vcc, exec, s[36:37]
	s_waitcnt vmcnt(1)
	v_cndmask_b32_e64 v89, 0, v133, s[0:1]
	s_cbranch_vccnz .LBB0_1098
	global_load_dword v93, v[90:91], off offset:240 nt
	s_waitcnt vmcnt(0)
	v_mul_f32_e32 v89, v89, v93
.LBB0_1098:
	ds_write_b32 v103, v89 offset:7920
	s_and_b64 vcc, exec, s[36:37]
	s_waitcnt vmcnt(0)
	v_cndmask_b32_e64 v89, 0, v92, s[0:1]
	s_cbranch_vccnz .LBB0_1100
	global_load_dword v90, v[90:91], off offset:248 nt
	s_waitcnt vmcnt(0)
	v_mul_f32_e32 v89, v89, v90

; __device__ __forceinline__ unsigned cvtpk(float lo, float hi) { const f32x2v v = {lo, hi}; return __builtin_bit_cast(unsigned, __builtin_convertvector(v, bf16x2v)); }
; __device__ __forceinline__ void p0_prologue(const Args& A, LAS unsigned char* ldsl, int wave, int lane, int G) {
;     ...
;     for (int m0 = gw; m0 < M; m0 += 2 * NGW) {
;         const int m1 = m0 + NGW; const bool two = m1 < M; const int m1c = two ? m1 : m0;
;         const float* s0 = (m0 < MP) ? A.in[I_XP] + (size_t)m0 * D : A.in[I_XS] + (size_t)(m0 - MP) * D;
;         const float* s1 = (m1c < MP) ? A.in[I_XP] + (size_t)m1c * D : A.in[I_XS] + (size_t)(m1c - MP) * D;
;         f32x4 v[2][4];
; #pragma unroll
;         for (int j = 0; j < 4; ++j) { v[0][j] = ((const f32x4*)s0 + lane)[64 * j]; v[1][j] = ((const f32x4*)s1 + lane)[64 * j]; }
; #pragma unroll
;         for (int h = 0; h < 2; ++h) {
;             const int m = h ? m1c : m0;
;             v2u* bo = (v2u*)(xb + (size_t)m * D) + lane; float s = 0.f;
; #pragma unroll
;             for (int j = 0; j < 4; ++j) { v2u w; w.x = cvtpk(v[h][j].x, v[h][j].y); w.y = cvtpk(v[h][j].z, v[h][j].w); if (h == 0 || two) bo[64 * j] = w;
;                 const float r0 = __builtin_bit_cast(float, w.x << 16), r1 = __builtin_bit_cast(float, w.x & 0xffff0000u), r2 = __builtin_bit_cast(float, w.y << 16), r3 = __builtin_bit_cast(float, w.y & 0xffff0000u);
;                 s += (r0 * r0 + r1 * r1) + (r2 * r2 + r3 * r3); }
;             s = wave_sum(s);
;             if (lane == 0 && (h == 0 || two)) rss[m] = s;
;         }
;     }
.LBB0_1111:
	s_add_i32 s3, s4, s96
	s_cmpk_lt_i32 s3, 0x4400
	s_cselect_b64 s[8:9], -1, 0
	s_and_b64 s[6:7], s[8:9], exec
	s_cselect_b32 s6, s3, s4
	s_add_i32 s7, s4, 0xffffc000
	s_ashr_i32 s5, s4, 31
	s_cmpk_lt_i32 s4, 0x4000
	v_readlane_b32 s36, v253, 19
	s_cselect_b32 s11, s5, 0
	s_cselect_b32 s10, s4, s7
	v_readlane_b32 s37, v253, 20
	v_readlane_b32 s38, v253, 21
	v_readlane_b32 s39, v253, 22
	s_cselect_b32 s7, s37, s39
	s_cselect_b32 s12, s36, s38
	s_lshl_b64 s[10:11], s[10:11], 12
	s_add_u32 s10, s12, s10
	s_addc_u32 s11, s7, s11
	global_load_dwordx4 v[30:33], v29, s[10:11] nt
	global_load_dwordx4 v[34:37], v29, s[10:11] offset:1024 nt
	global_load_dwordx4 v[38:41], v29, s[10:11] offset:2048 nt
	global_load_dwordx4 v[42:45], v29, s[10:11] offset:3072 nt
	s_add_i32 s10, s6, 0xffffc000
	s_ashr_i32 s7, s6, 31
	s_cmpk_lt_i32 s6, 0x4000
	s_cselect_b32 s11, s7, 0
	s_cselect_b32 s10, s6, s10
	s_cselect_b32 s12, s37, s39
	s_cselect_b32 s13, s36, s38
	s_lshl_b64 s[10:11], s[10:11], 12
	s_add_u32 s10, s13, s10
	s_addc_u32 s11, s12, s11
	s_waitcnt lgkmcnt(0)
	global_load_dwordx4 v[18:21], v29, s[10:11] nt
	global_load_dwordx4 v[14:17], v29, s[10:11] offset:1024 nt
	global_load_dwordx4 v[10:13], v29, s[10:11] offset:2048 nt
	global_load_dwordx4 v[6:9], v29, s[10:11] offset:3072 nt
	s_lshl_b64 s[10:11], s[4:5], 11
	v_readlane_b32 s40, v253, 23
	v_readlane_b32 s41, v253, 24
	v_readlane_b32 s42, v253, 25
	v_readlane_b32 s43, v253, 26
	v_readlane_b32 s44, v253, 27
	v_readlane_b32 s45, v253, 28
	v_readlane_b32 s46, v253, 29
	v_readlane_b32 s47, v253, 30
	v_readlane_b32 s48, v253, 31
	v_readlane_b32 s49, v253, 32
	v_readlane_b32 s50, v253, 33
	v_readlane_b32 s51, v253, 34
	s_waitcnt vmcnt(7)
	v_cvt_pk_bf16_f32 v30, v30, v31
	v_cvt_pk_bf16_f32 v31, v32, v33
	s_waitcnt vmcnt(6)
	v_cvt_pk_bf16_f32 v32, v34, v35
	v_cvt_pk_bf16_f32 v33, v36, v37
	s_waitcnt vmcnt(5)
	v_cvt_pk_bf16_f32 v34, v38, v39
	v_cvt_pk_bf16_f32 v35, v40, v41
	s_waitcnt vmcnt(4)
	v_cvt_pk_bf16_f32 v36, v42, v43
	v_and_b32_e32 v23, 0xffff0000, v30
	v_and_b32_e32 v39, 0xffff0000, v31
	v_and_b32_e32 v41, 0xffff0000, v32
	v_and_b32_e32 v43, 0xffff0000, v33
	v_cvt_pk_bf16_f32 v37, v44, v45
	v_lshlrev_b32_e32 v22, 16, v30
	v_lshlrev_b32_e32 v38, 16, v31
	v_lshlrev_b32_e32 v40, 16, v32
	v_lshlrev_b32_e32 v42, 16, v33
	v_and_b32_e32 v45, 0xffff0000, v34
	v_and_b32_e32 v47, 0xffff0000, v35
	v_mul_f32_e32 v23, v23, v23
	v_mul_f32_e32 v39, v39, v39
	v_mul_f32_e32 v41, v41, v41
	v_mul_f32_e32 v43, v43, v43
	v_lshlrev_b32_e32 v44, 16, v34
	v_lshlrev_b32_e32 v46, 16, v35
	v_and_b32_e32 v49, 0xffff0000, v36
	v_and_b32_e32 v51, 0xffff0000, v37
	v_mul_f32_e32 v45, v45, v45
	v_mul_f32_e32 v47, v47, v47
	v_fmac_f32_e32 v23, v22, v22
	v_fmac_f32_e32 v39, v38, v38
	v_fmac_f32_e32 v41, v40, v40
	v_fmac_f32_e32 v43, v42, v42
	v_lshlrev_b32_e32 v48, 16, v36
	v_lshlrev_b32_e32 v50, 16, v37
	v_mul_f32_e32 v49, v49, v49
	v_mul_f32_e32 v51, v51, v51
	v_fmac_f32_e32 v45, v44, v44
	v_fmac_f32_e32 v47, v46, v46
	v_add_f32_e32 v22, v23, v39
	v_add_f32_e32 v23, v41, v43
	v_fmac_f32_e32 v49, v48, v48
	v_fmac_f32_e32 v51, v50, v50
	v_add_f32_e32 v38, v45, v47
	v_add_f32_e32 v22, v22, v23
	v_add_f32_e32 v22, v22, v38
	v_add_f32_e32 v23, v49, v51
	v_add_f32_e32 v22, v22, v23
	ds_bpermute_b32 v23, v5, v22
	v_lshl_add_u64 v[38:39], v[2:3], 0, s[10:11]
	global_store_dwordx2 v[38:39], v[30:31], off
	global_store_dwordx2 v[38:39], v[32:33], off offset:512
	global_store_dwordx2 v[38:39], v[34:35], off offset:1024
	global_store_dwordx2 v[38:39], v[36:37], off offset:1536
	s_waitcnt lgkmcnt(0)
	v_add_f32_e32 v22, v22, v23
	ds_bpermute_b32 v23, v24, v22
	s_waitcnt lgkmcnt(0)
	v_add_f32_e32 v22, v22, v23
	ds_bpermute_b32 v23, v25, v22
	s_waitcnt lgkmcnt(0)
	v_add_f32_e32 v22, v22, v23
	ds_bpermute_b32 v23, v26, v22
	s_waitcnt lgkmcnt(0)
	v_add_f32_e32 v22, v22, v23
	ds_bpermute_b32 v23, v27, v22
	s_waitcnt lgkmcnt(0)
	v_add_f32_e32 v22, v22, v23
	ds_bpermute_b32 v23, v28, v22
	s_and_saveexec_b64 s[10:11], s[0:1]
	s_cbranch_execz .LBB0_1113
	s_lshl_b64 s[4:5], s[4:5], 2
	s_add_u32 s4, s88, s4
	s_waitcnt lgkmcnt(0)
	v_add_f32_e32 v22, v22, v23
	s_addc_u32 s5, s89, s5
	global_store_dword v4, v22, s[4:5]
